# attn_prio
# baseline (speedup 1.0000x reference)
; template <bool BAND>
; __device__ __forceinline__ void attn_body(const u16* Qb, const u16* __restrict__ Kh, const u16* __restrict__ Vh, u16* Ob, int NT, int kpos0, int qpos0, float sink_l2, char* lds, const float* __restrict__ qn) {
;   const int tid = otid(), wid = tid >> 6, lane = tid & 63, r32 = lane & 31, hi = lane >> 5;
;   u16* V_lds = (u16*)lds; u16* K_lds = (u16*)(lds + 2 * SHM_V);
;   float* ws = (float*)(lds + 2 * SHM_V + 2 * SHM_K) + wid * 64; float* li_l = ws; float* al_l = ws + 32;
;   float m_reg = -1e30f, l_reg = 0; f32x16 o[4] = {}; bf16x8 qr[8];
;   const u16* Qw = Qb + (long)(wid * QBLK + r32) * LDQ + hi * 8;
; #pragma unroll
;   for (int d0 = 0; d0 < 8; ++d0) qr[d0] = *reinterpret_cast<const bf16x8*>(Qw + d0 * 16);
;   { float qf[8][8]; float ss = 0.f;
; #pragma unroll
;     for (int d0 = 0; d0 < 8; ++d0)
; #pragma unroll
;       for (int e = 0; e < 8; ++e) { qf[d0][e] = bf2f(qr[d0][e]); ss += qf[d0][e] * qf[d0][e]; }
;     { auto rr = __builtin_amdgcn_permlane32_swap(__float_as_uint(ss), __float_as_uint(ss), false, false);
;       ss = __uint_as_float(rr[0]) + __uint_as_float(rr[1]); }
;     const float rs = rsqrtf(ss * (1.f / 128.f) + 1e-6f);
; #pragma unroll
;     for (int d0 = 0; d0 < 8; ++d0) {
;       const f32x4 g0 = *reinterpret_cast<const f32x4*>(qn + d0 * 16 + hi * 8), g1 = *reinterpret_cast<const f32x4*>(qn + d0 * 16 + hi * 8 + 4);
; #pragma unroll
;       for (int e = 0; e < 4; ++e) { qf[d0][e] *= rs * g0[e]; qf[d0][e + 4] *= rs * g1[e]; }
;     }
;     const int pos = qpos0 + wid * QBLK + r32;
;     if constexpr (BAND) {
; #pragma unroll
;       for (int e = 0; e < 8; ++e) {
;         const float frv = exp2f(-(float)(hi * 8 + e) * (1.f / 16.f) * 18.931568569324174f) * 0.15915494309189535f;
;         float r = (float)pos * frv; r = r - floorf(r);
;         const float sn = __builtin_amdgcn_sinf(r), cs = __builtin_amdgcn_cosf(r);
;         const float x1 = qf[0][e], x2 = qf[1][e];
;         qf[0][e] = x1 * cs - x2 * sn; qf[1][e] = x2 * cs + x1 * sn;
;       }
;     } else {
;       const float prow = (float)(pos >> 6), pcol = (float)(pos & 63);
; #pragma unroll
;       for (int dp = 0; dp < 2; ++dp)
; #pragma unroll
;         for (int e = 0; e < 8; ++e) {
;           const float frv = exp2f(-(float)(dp * 16 + hi * 8 + e) * (1.f / 32.f) * 13.287712379549449f) * 0.15915494309189535f;
.LBB0_1643:
	s_and_b32 s6, s20, s6
	s_lshl_b32 s21, s6, 8
	s_add_i32 s6, s8, s21
	s_ashr_i32 s7, s6, 31
	s_and_b32 s9, s18, 7
	s_lshl_b64 s[6:7], s[6:7], 11
	s_add_u32 s6, s10, s6
	s_addc_u32 s7, s11, s7
	s_lshl_b32 s9, s9, 8
	s_add_u32 s6, s6, s9
	s_addc_u32 s7, s7, 0
	s_add_u32 s16, s6, 0x16800000
	s_addc_u32 s17, s7, 0
	s_ashr_i32 s9, s8, 31
	s_lshl_b64 s[6:7], s[8:9], 9
	s_add_u32 s6, s10, s6
	s_addc_u32 s7, s11, s7
	s_lshl_b32 s18, s18, 6
	s_and_b32 s24, s18, 0x100
	s_add_u32 s6, s6, s24
	s_addc_u32 s7, s7, 0
	s_add_u32 s18, s6, 0x1e800000
	s_addc_u32 s19, s7, 0
	s_add_u32 s6, s6, 0x20800000
	v_readfirstlane_b32 s22, v224
	s_addc_u32 s7, s7, 0
	s_andn2_b32 s22, s22, 63
	v_add_u32_e32 v247, s22, v225
	s_load_dwordx2 s[26:27], s[12:13], 0x80
	s_movk_i32 s22, 0xffe0
	v_and_b32_e32 v246, 31, v247
	v_ashrrev_i32_e32 v0, 1, v247
	v_and_b32_e32 v176, 0xffffffe0, v0
	v_or_b32_e32 v96, s21, v246
	v_bfe_u32 v245, v247, 5, 1
	v_add_u32_e32 v96, v96, v176
	v_lshlrev_b32_e32 v156, 3, v245
	v_ashrrev_i32_e32 v97, 6, v96
	v_cvt_f32_i32_e32 v157, v97
	v_cvt_f32_ubyte0_e32 v97, v156
	v_mul_f32_e32 v97, 0xbd000000, v97
	v_mul_f32_e32 v98, 0x41549a78, v97
	s_mov_b32 s21, 0xc2fc0000
	v_cmp_gt_f32_e32 vcc, s21, v98
	v_and_b32_e32 v96, 63, v96
	v_cvt_f32_ubyte0_e32 v164, v96
	v_cndmask_b32_e32 v98, 0, v252, vcc
	v_fmac_f32_e32 v98, 0x41549a78, v97
	v_exp_f32_e32 v97, v98
	v_cndmask_b32_e32 v96, 0, v250, vcc
	v_bfi_b32 v0, s22, v0, v247
	v_ashrrev_i32_e32 v1, 31, v0
	v_ldexp_f32 v96, v97, v96
	v_mul_f32_e32 v98, 0.15915494, v96
	v_mul_f32_e32 v96, v98, v157
	v_mul_f32_e32 v99, v98, v164
	v_floor_f32_e32 v96, v96
	v_floor_f32_e32 v99, v99
	v_fma_f32 v97, v98, v157, -v96
	v_fma_f32 v99, v98, v164, -v99
	v_or_b32_e32 v98, 1, v156
	v_cvt_f32_ubyte0_e32 v98, v98
	v_mul_f32_e32 v98, 0xbd000000, v98
	v_mul_f32_e32 v100, 0x41549a78, v98
	v_cmp_gt_f32_e32 vcc, s21, v100
	v_lshlrev_b64 v[0:1], 11, v[0:1]
	v_lshl_add_u64 v[0:1], s[16:17], 0, v[0:1]
	v_cndmask_b32_e32 v100, 0, v252, vcc
	v_fmac_f32_e32 v100, 0x41549a78, v98
	v_exp_f32_e32 v100, v100
	v_cndmask_b32_e32 v101, 0, v250, vcc
	v_lshlrev_b32_e32 v180, 4, v245
	v_lshl_add_u64 v[0:1], v[0:1], 0, v[180:181]
	v_ldexp_f32 v100, v100, v101
	v_mul_f32_e32 v102, 0.15915494, v100
	v_mul_f32_e32 v100, v102, v157
	v_mul_f32_e32 v103, v102, v164
	v_floor_f32_e32 v100, v100
	v_floor_f32_e32 v103, v103
	v_fma_f32 v100, v102, v157, -v100
	v_fma_f32 v102, v102, v164, -v103
	v_or_b32_e32 v103, 2, v156
	v_cvt_f32_ubyte0_e32 v103, v103
	v_mul_f32_e32 v103, 0xbd000000, v103
	v_mul_f32_e32 v104, 0x41549a78, v103
	v_cmp_gt_f32_e32 vcc, s21, v104
	v_sin_f32_e32 v105, v102
	global_load_dwordx4 v[36:39], v[0:1], off
	global_load_dwordx4 v[48:51], v[0:1], off offset:32
	global_load_dwordx4 v[40:43], v[0:1], off offset:64
	global_load_dwordx4 v[52:55], v[0:1], off offset:96
	global_load_dwordx4 v[64:67], v[0:1], off offset:128
	global_load_dwordx4 v[80:83], v[0:1], off offset:160
	global_load_dwordx4 v[68:71], v[0:1], off offset:192
	global_load_dwordx4 v[84:87], v[0:1], off offset:224
	v_cndmask_b32_e32 v104, 0, v252, vcc
	v_fmac_f32_e32 v104, 0x41549a78, v103
	v_exp_f32_e32 v103, v104
	v_cos_f32_e32 v104, v102
	v_cndmask_b32_e32 v102, 0, v250, vcc
	v_and_b32_e32 v0, 32, v247
	v_ldexp_f32 v102, v103, v102
	v_mul_f32_e32 v106, 0.15915494, v102
	v_mul_f32_e32 v102, v106, v157
	v_mul_f32_e32 v107, v106, v164
	v_floor_f32_e32 v102, v102
	v_floor_f32_e32 v107, v107
	v_fma_f32 v103, v106, v157, -v102
	v_fma_f32 v107, v106, v164, -v107
	v_or_b32_e32 v106, 3, v156
	v_cvt_f32_ubyte0_e32 v106, v106
	v_mul_f32_e32 v106, 0xbd000000, v106
	v_mul_f32_e32 v108, 0x41549a78, v106
	v_cmp_gt_f32_e32 vcc, s21, v108
	s_waitcnt lgkmcnt(0)
	global_load_dwordx4 v[32:35], v0, s[26:27]
	global_load_dwordx4 v[44:47], v0, s[26:27] offset:16
	global_load_dwordx4 v[56:59], v0, s[26:27] offset:64
	global_load_dwordx4 v[60:63], v0, s[26:27] offset:80
	global_load_dwordx4 v[28:31], v0, s[26:27] offset:128
	global_load_dwordx4 v[24:27], v0, s[26:27] offset:144
	global_load_dwordx4 v[20:23], v0, s[26:27] offset:192
	global_load_dwordx4 v[16:19], v0, s[26:27] offset:208
	global_load_dwordx4 v[72:75], v0, s[26:27] offset:256
	global_load_dwordx4 v[76:79], v0, s[26:27] offset:272
	global_load_dwordx4 v[88:91], v0, s[26:27] offset:320
	global_load_dwordx4 v[92:95], v0, s[26:27] offset:336
	global_load_dwordx4 v[12:15], v0, s[26:27] offset:384
	global_load_dwordx4 v[8:11], v0, s[26:27] offset:400
	global_load_dwordx4 v[4:7], v0, s[26:27] offset:448
	s_nop 0
	global_load_dwordx4 v[0:3], v0, s[26:27] offset:464
	v_cndmask_b32_e32 v108, 0, v252, vcc
	v_fmac_f32_e32 v108, 0x41549a78, v106
	v_exp_f32_e32 v108, v108
	v_cndmask_b32_e32 v109, 0, v250, vcc
	v_sin_f32_e32 v96, v97
	v_cos_f32_e32 v97, v97
	v_ldexp_f32 v108, v108, v109
	v_mul_f32_e32 v110, 0.15915494, v108
	v_mul_f32_e32 v108, v110, v157
	v_mul_f32_e32 v111, v110, v164
	v_floor_f32_e32 v108, v108
	v_floor_f32_e32 v111, v111
	v_fma_f32 v108, v110, v157, -v108
	v_fma_f32 v110, v110, v164, -v111
	v_or_b32_e32 v111, 4, v156
	v_cvt_f32_ubyte0_e32 v111, v111
	v_mul_f32_e32 v111, 0xbd000000, v111
	v_mul_f32_e32 v112, 0x41549a78, v111
	v_cmp_gt_f32_e32 vcc, s21, v112
	v_sin_f32_e32 v113, v110
	v_sin_f32_e32 v98, v99
	v_cndmask_b32_e32 v112, 0, v252, vcc
	v_fmac_f32_e32 v112, 0x41549a78, v111
	v_exp_f32_e32 v111, v112
	v_cos_f32_e32 v112, v110
	v_cndmask_b32_e32 v110, 0, v250, vcc
	v_cos_f32_e32 v99, v99
	v_ldexp_f32 v110, v111, v110
	v_mul_f32_e32 v114, 0.15915494, v110
	v_mul_f32_e32 v110, v114, v157
	v_mul_f32_e32 v115, v114, v164
	v_floor_f32_e32 v110, v110
	v_floor_f32_e32 v115, v115
	v_fma_f32 v111, v114, v157, -v110
	v_fma_f32 v115, v114, v164, -v115
	v_or_b32_e32 v114, 5, v156
	v_cvt_f32_ubyte0_e32 v114, v114
	v_mul_f32_e32 v114, 0xbd000000, v114
	v_mul_f32_e32 v116, 0x41549a78, v114
	v_cmp_gt_f32_e32 vcc, s21, v116
	v_sin_f32_e32 v101, v100
	v_cos_f32_e32 v100, v100
	v_cndmask_b32_e32 v116, 0, v252, vcc
	v_fmac_f32_e32 v116, 0x41549a78, v114
	v_exp_f32_e32 v116, v116
	v_cndmask_b32_e32 v117, 0, v250, vcc
	v_mov_b32_e32 v200, v99
	v_mov_b32_e32 v201, v98
	v_ldexp_f32 v116, v116, v117
	v_mul_f32_e32 v118, 0.15915494, v116
	v_mul_f32_e32 v116, v118, v157
	v_mul_f32_e32 v119, v118, v164
	v_floor_f32_e32 v116, v116
	v_floor_f32_e32 v119, v119
	v_fma_f32 v116, v118, v157, -v116
	v_fma_f32 v118, v118, v164, -v119
	v_or_b32_e32 v119, 6, v156
	v_cvt_f32_ubyte0_e32 v119, v119
	v_mul_f32_e32 v119, 0xbd000000, v119
	v_mul_f32_e32 v120, 0x41549a78, v119
	v_cmp_gt_f32_e32 vcc, s21, v120
	v_sin_f32_e32 v121, v118
	s_waitcnt vmcnt(20)
; __device__ __forceinline__ float bf2f(short v) { return __uint_as_float(((unsigned)(unsigned short)v) << 16); }
; template <bool BAND>
; __device__ __forceinline__ void attn_body(const u16* Qb, const u16* __restrict__ Kh, const u16* __restrict__ Vh, u16* Ob, int NT, int kpos0, int qpos0, float sink_l2, char* lds, const float* __restrict__ qn) {
;     ...
;   { float qf[8][8]; float ss = 0.f;
; #pragma unroll
;     for (int d0 = 0; d0 < 8; ++d0)
; #pragma unroll
;       for (int e = 0; e < 8; ++e) { qf[d0][e] = bf2f(qr[d0][e]); ss += qf[d0][e] * qf[d0][e]; }
;     { auto rr = __builtin_amdgcn_permlane32_swap(__float_as_uint(ss), __float_as_uint(ss), false, false);
;       ss = __uint_as_float(rr[0]) + __uint_as_float(rr[1]); }
;     const float rs = rsqrtf(ss * (1.f / 128.f) + 1e-6f);
; #pragma unroll
;     for (int d0 = 0; d0 < 8; ++d0) {
;       const f32x4 g0 = *reinterpret_cast<const f32x4*>(qn + d0 * 16 + hi * 8), g1 = *reinterpret_cast<const f32x4*>(qn + d0 * 16 + hi * 8 + 4);
; #pragma unroll
;       for (int e = 0; e < 4; ++e) { qf[d0][e] *= rs * g0[e]; qf[d0][e + 4] *= rs * g1[e]; }
;     }
;     const int pos = qpos0 + wid * QBLK + r32;
;     if constexpr (BAND) {
; #pragma unroll
;       for (int e = 0; e < 8; ++e) {
;         const float frv = exp2f(-(float)(hi * 8 + e) * (1.f / 16.f) * 18.931568569324174f) * 0.15915494309189535f;
;         float r = (float)pos * frv; r = r - floorf(r);
;         const float sn = __builtin_amdgcn_sinf(r), cs = __builtin_amdgcn_cosf(r);
;         const float x1 = qf[0][e], x2 = qf[1][e];
;         qf[0][e] = x1 * cs - x2 * sn; qf[1][e] = x2 * cs + x1 * sn;
;       }
;     } else {
;       const float prow = (float)(pos >> 6), pcol = (float)(pos & 63);
; #pragma unroll
;       for (int dp = 0; dp < 2; ++dp)
; #pragma unroll
;         for (int e = 0; e < 8; ++e) {
;           const float frv = exp2f(-(float)(dp * 16 + hi * 8 + e) * (1.f / 32.f) * 13.287712379549449f) * 0.15915494309189535f;
;           float r = prow * frv; r = r - floorf(r);
;           float sn = __builtin_amdgcn_sinf(r), cs = __builtin_amdgcn_cosf(r);
;           float x1 = qf[dp][e], x2 = qf[dp + 2][e];
;           qf[dp][e] = x1 * cs - x2 * sn; qf[dp + 2][e] = x2 * cs + x1 * sn;
	v_lshlrev_b32_e32 v215, 16, v55
	v_cndmask_b32_e32 v120, 0, v252, vcc
	v_fmac_f32_e32 v120, 0x41549a78, v119
	v_exp_f32_e32 v119, v120
	v_cos_f32_e32 v120, v118
	v_cndmask_b32_e32 v118, 0, v250, vcc
	v_and_b32_e32 v219, 0xffff0000, v55
	v_ldexp_f32 v118, v119, v118
	v_mul_f32_e32 v122, 0.15915494, v118
	v_mul_f32_e32 v118, v122, v157
	v_mul_f32_e32 v123, v122, v164
	v_floor_f32_e32 v118, v118
	v_floor_f32_e32 v123, v123
	v_fma_f32 v119, v122, v157, -v118
	v_fma_f32 v123, v122, v164, -v123
	v_or_b32_e32 v122, 7, v156
	v_cvt_f32_ubyte0_e32 v122, v122
	v_mul_f32_e32 v122, 0xbd000000, v122
	v_mul_f32_e32 v124, 0x41549a78, v122
	v_cmp_gt_f32_e32 vcc, s21, v124
	s_waitcnt vmcnt(8)
	v_mov_b32_e32 v221, v16
	v_mov_b32_e32 v16, v61
	v_cndmask_b32_e32 v124, 0, v252, vcc
	v_fmac_f32_e32 v124, 0x41549a78, v122
	v_exp_f32_e32 v124, v124
	v_cndmask_b32_e32 v125, 0, v250, vcc
	v_lshlrev_b32_e32 v55, 16, v53
	v_and_b32_e32 v61, 0xffff0000, v53
	v_ldexp_f32 v124, v124, v125
	v_mul_f32_e32 v126, 0.15915494, v124
	v_mul_f32_e32 v124, v126, v157
	v_mul_f32_e32 v127, v126, v164
	v_floor_f32_e32 v124, v124
	v_floor_f32_e32 v127, v127
	v_fma_f32 v124, v126, v157, -v124
	v_fma_f32 v126, v126, v164, -v127
	v_or_b32_e32 v127, 16, v156
	v_cvt_f32_ubyte0_e32 v127, v127
	v_mul_f32_e32 v127, 0xbd000000, v127
	v_mul_f32_e32 v128, 0x41549a78, v127
	v_cmp_gt_f32_e32 vcc, s21, v128
	v_sin_f32_e32 v129, v126
	v_lshlrev_b32_e32 v53, 16, v43
	v_cndmask_b32_e32 v128, 0, v252, vcc
	v_fmac_f32_e32 v128, 0x41549a78, v127
	v_exp_f32_e32 v127, v128
	v_cos_f32_e32 v128, v126
	v_cndmask_b32_e32 v126, 0, v250, vcc
	v_and_b32_e32 v231, 0xffff0000, v43
	v_ldexp_f32 v126, v127, v126
	v_mul_f32_e32 v130, 0.15915494, v126
	v_mul_f32_e32 v126, v130, v157
	v_mul_f32_e32 v131, v130, v164
	v_floor_f32_e32 v126, v126
	v_floor_f32_e32 v131, v131
	v_fma_f32 v127, v130, v157, -v126
	v_fma_f32 v131, v130, v164, -v131
	v_or_b32_e32 v130, 17, v156
	v_cvt_f32_ubyte0_e32 v130, v130
	v_mul_f32_e32 v130, 0xbd000000, v130
	v_mul_f32_e32 v132, 0x41549a78, v130
	v_cmp_gt_f32_e32 vcc, s21, v132
	v_mov_b32_e32 v233, v24
	v_mov_b32_e32 v24, v45
	v_cndmask_b32_e32 v132, 0, v252, vcc
	v_fmac_f32_e32 v132, 0x41549a78, v130
	v_exp_f32_e32 v132, v132
	v_cndmask_b32_e32 v133, 0, v250, vcc
	v_lshlrev_b32_e32 v43, 16, v41
	v_and_b32_e32 v45, 0xffff0000, v41
	v_ldexp_f32 v132, v132, v133
	v_mul_f32_e32 v134, 0.15915494, v132
	v_mul_f32_e32 v132, v134, v157
	v_mul_f32_e32 v135, v134, v164
	v_floor_f32_e32 v132, v132
	v_floor_f32_e32 v135, v135
	v_fma_f32 v132, v134, v157, -v132
	v_fma_f32 v134, v134, v164, -v135
	v_or_b32_e32 v135, 18, v156
	v_cvt_f32_ubyte0_e32 v135, v135
	v_mul_f32_e32 v135, 0xbd000000, v135
	v_mul_f32_e32 v136, 0x41549a78, v135
	v_cmp_gt_f32_e32 vcc, s21, v136
	v_sin_f32_e32 v137, v134
	v_lshlrev_b32_e32 v235, 16, v40
	v_cndmask_b32_e32 v136, 0, v252, vcc
	v_fmac_f32_e32 v136, 0x41549a78, v135
	v_exp_f32_e32 v135, v136
	v_cos_f32_e32 v136, v134
	v_cndmask_b32_e32 v134, 0, v250, vcc
	v_and_b32_e32 v41, 0xffff0000, v40
	v_ldexp_f32 v134, v135, v134
	v_mul_f32_e32 v138, 0.15915494, v134
	v_mul_f32_e32 v134, v138, v157
	v_mul_f32_e32 v139, v138, v164
	v_floor_f32_e32 v134, v134
	v_floor_f32_e32 v139, v139
	v_fma_f32 v135, v138, v157, -v134
	v_fma_f32 v139, v138, v164, -v139
	v_or_b32_e32 v138, 19, v156
	v_cvt_f32_ubyte0_e32 v138, v138
	v_mul_f32_e32 v138, 0xbd000000, v138
	v_mul_f32_e32 v140, 0x41549a78, v138
	v_cmp_gt_f32_e32 vcc, s21, v140
	v_and_b32_e32 v40, 0xffff0000, v36
	v_lshlrev_b32_e32 v234, 16, v36
	v_cndmask_b32_e32 v140, 0, v252, vcc
	v_fmac_f32_e32 v140, 0x41549a78, v138
	v_exp_f32_e32 v140, v140
	v_cndmask_b32_e32 v141, 0, v250, vcc
	v_pk_mul_f32 v[236:237], v[40:41], v[40:41]
	v_lshlrev_b32_e32 v214, 16, v51
	v_ldexp_f32 v140, v140, v141
	v_mul_f32_e32 v142, 0.15915494, v140
	v_mul_f32_e32 v140, v142, v157
	v_mul_f32_e32 v143, v142, v164
	v_floor_f32_e32 v140, v140
	v_floor_f32_e32 v143, v143
	v_fma_f32 v140, v142, v157, -v140
	v_fma_f32 v142, v142, v164, -v143
	v_or_b32_e32 v143, 20, v156
	v_cvt_f32_ubyte0_e32 v143, v143
	v_mul_f32_e32 v143, 0xbd000000, v143
	v_mul_f32_e32 v144, 0x41549a78, v143
	v_cmp_gt_f32_e32 vcc, s21, v144
	v_sin_f32_e32 v145, v142
	v_mov_b32_e32 v217, v18
	v_cndmask_b32_e32 v144, 0, v252, vcc
	v_fmac_f32_e32 v144, 0x41549a78, v143
	v_exp_f32_e32 v143, v144
	v_cos_f32_e32 v144, v142
	v_cndmask_b32_e32 v142, 0, v250, vcc
	v_and_b32_e32 v218, 0xffff0000, v51
	v_ldexp_f32 v142, v143, v142
	v_mul_f32_e32 v146, 0.15915494, v142
	v_mul_f32_e32 v142, v146, v157
	v_mul_f32_e32 v147, v146, v164
	v_mov_b32_e32 v18, v63
	v_lshlrev_b32_e32 v63, 16, v54
	v_mov_b32_e32 v220, v60
	v_and_b32_e32 v51, 0xffff0000, v54
	v_lshlrev_b32_e32 v54, 16, v49
	v_mov_b32_e32 v223, v22
	v_and_b32_e32 v60, 0xffff0000, v49
	v_mov_b32_e32 v22, v59
	v_lshlrev_b32_e32 v59, 16, v52
	v_mov_b32_e32 v227, v20
	v_and_b32_e32 v49, 0xffff0000, v52
	v_mov_b32_e32 v20, v57
	v_lshlrev_b32_e32 v52, 16, v39
	v_mov_b32_e32 v57, v26
	v_and_b32_e32 v230, 0xffff0000, v39
	v_mov_b32_e32 v26, v47
	v_lshlrev_b32_e32 v47, 16, v42
	v_mov_b32_e32 v232, v44
	v_and_b32_e32 v39, 0xffff0000, v42
	v_lshlrev_b32_e32 v42, 16, v37
	v_and_b32_e32 v44, 0xffff0000, v37
	v_pk_fma_f32 v[36:37], v[234:235], v[234:235], v[236:237]
	v_floor_f32_e32 v142, v142
	v_floor_f32_e32 v147, v147
	v_pk_fma_f32 v[36:37], v[42:43], v[42:43], v[36:37]
	v_fma_f32 v143, v146, v157, -v142
	v_fma_f32 v147, v146, v164, -v147
	v_or_b32_e32 v146, 21, v156
	v_mov_b32_e32 v226, v56
	v_mov_b32_e32 v56, v46
	v_lshlrev_b32_e32 v46, 16, v38
	v_pk_fma_f32 v[36:37], v[44:45], v[44:45], v[36:37]
	v_cvt_f32_ubyte0_e32 v146, v146
	v_and_b32_e32 v38, 0xffff0000, v38
; __device__ __forceinline__ float bf2f(short v) { return __uint_as_float(((unsigned)(unsigned short)v) << 16); }
; template <bool BAND>
; __device__ __forceinline__ void attn_body(const u16* Qb, const u16* __restrict__ Kh, const u16* __restrict__ Vh, u16* Ob, int NT, int kpos0, int qpos0, float sink_l2, char* lds, const float* __restrict__ qn) {
;     ...
;   { float qf[8][8]; float ss = 0.f;
; #pragma unroll
;     for (int d0 = 0; d0 < 8; ++d0)
; #pragma unroll
;       for (int e = 0; e < 8; ++e) { qf[d0][e] = bf2f(qr[d0][e]); ss += qf[d0][e] * qf[d0][e]; }
;     { auto rr = __builtin_amdgcn_permlane32_swap(__float_as_uint(ss), __float_as_uint(ss), false, false);
;       ss = __uint_as_float(rr[0]) + __uint_as_float(rr[1]); }
;     const float rs = rsqrtf(ss * (1.f / 128.f) + 1e-6f);
; #pragma unroll
;     for (int d0 = 0; d0 < 8; ++d0) {
;       const f32x4 g0 = *reinterpret_cast<const f32x4*>(qn + d0 * 16 + hi * 8), g1 = *reinterpret_cast<const f32x4*>(qn + d0 * 16 + hi * 8 + 4);
; #pragma unroll
;       for (int e = 0; e < 4; ++e) { qf[d0][e] *= rs * g0[e]; qf[d0][e + 4] *= rs * g1[e]; }
;     }
;     const int pos = qpos0 + wid * QBLK + r32;
;     if constexpr (BAND) {
; #pragma unroll
;       for (int e = 0; e < 8; ++e) {
;         const float frv = exp2f(-(float)(hi * 8 + e) * (1.f / 16.f) * 18.931568569324174f) * 0.15915494309189535f;
;         float r = (float)pos * frv; r = r - floorf(r);
;         const float sn = __builtin_amdgcn_sinf(r), cs = __builtin_amdgcn_cosf(r);
;         const float x1 = qf[0][e], x2 = qf[1][e];
;         qf[0][e] = x1 * cs - x2 * sn; qf[1][e] = x2 * cs + x1 * sn;
;       }
;     } else {
;       const float prow = (float)(pos >> 6), pcol = (float)(pos & 63);
; #pragma unroll
;       for (int dp = 0; dp < 2; ++dp)
; #pragma unroll
;         for (int e = 0; e < 8; ++e) {
;           const float frv = exp2f(-(float)(dp * 16 + hi * 8 + e) * (1.f / 32.f) * 13.287712379549449f) * 0.15915494309189535f;
;           float r = prow * frv; r = r - floorf(r);
;           float sn = __builtin_amdgcn_sinf(r), cs = __builtin_amdgcn_cosf(r);
;           float x1 = qf[dp][e], x2 = qf[dp + 2][e];
;           qf[dp][e] = x1 * cs - x2 * sn; qf[dp + 2][e] = x2 * cs + x1 * sn;
	v_pk_fma_f32 v[36:37], v[46:47], v[46:47], v[36:37]
	v_mul_f32_e32 v146, 0xbd000000, v146
	v_pk_fma_f32 v[36:37], v[38:39], v[38:39], v[36:37]
	v_mul_f32_e32 v148, 0x41549a78, v146
	v_pk_fma_f32 v[36:37], v[52:53], v[52:53], v[36:37]
	v_cmp_gt_f32_e32 vcc, s21, v148
	v_mov_b32_e32 v222, v58
	v_lshlrev_b32_e32 v58, 16, v48
	v_pk_fma_f32 v[36:37], v[230:231], v[230:231], v[36:37]
	v_cndmask_b32_e32 v148, 0, v252, vcc
	v_and_b32_e32 v48, 0xffff0000, v48
	v_pk_fma_f32 v[36:37], v[58:59], v[58:59], v[36:37]
	v_fmac_f32_e32 v148, 0x41549a78, v146
	v_pk_fma_f32 v[36:37], v[48:49], v[48:49], v[36:37]
	v_exp_f32_e32 v148, v148
	v_pk_fma_f32 v[36:37], v[54:55], v[54:55], v[36:37]
	v_mov_b32_e32 v216, v62
	v_lshlrev_b32_e32 v62, 16, v50
	v_pk_fma_f32 v[36:37], v[60:61], v[60:61], v[36:37]
	v_and_b32_e32 v50, 0xffff0000, v50
	v_pk_fma_f32 v[36:37], v[62:63], v[62:63], v[36:37]
	v_cndmask_b32_e32 v149, 0, v250, vcc
	v_pk_fma_f32 v[36:37], v[50:51], v[50:51], v[36:37]
	v_ldexp_f32 v148, v148, v149
	v_pk_fma_f32 v[36:37], v[214:215], v[214:215], v[36:37]
	v_mul_f32_e32 v150, 0.15915494, v148
	v_pk_fma_f32 v[36:37], v[218:219], v[218:219], v[36:37]
	v_mul_f32_e32 v238, v235, v235
	v_mul_f32_e32 v148, v150, v157
	v_mul_f32_e32 v151, v150, v164
	v_pk_add_f32 v[238:239], v[238:239], v[36:37] op_sel_hi:[0,1]
	v_floor_f32_e32 v148, v148
	v_floor_f32_e32 v151, v151
	v_pk_add_f32 v[236:237], v[236:237], v[238:239] op_sel:[1,0] op_sel_hi:[0,1]
	v_mul_f32_e32 v238, v43, v43
	v_fma_f32 v148, v150, v157, -v148
	v_fma_f32 v150, v150, v164, -v151
	v_or_b32_e32 v151, 22, v156
	v_pk_add_f32 v[236:237], v[238:239], v[236:237] op_sel_hi:[0,1]
	v_mul_f32_e32 v238, v45, v45
	v_cvt_f32_ubyte0_e32 v151, v151
	v_pk_add_f32 v[236:237], v[238:239], v[236:237] op_sel_hi:[0,1]
	v_mul_f32_e32 v238, v47, v47
	v_mul_f32_e32 v151, 0xbd000000, v151
	v_pk_add_f32 v[236:237], v[238:239], v[236:237] op_sel_hi:[0,1]
	v_mul_f32_e32 v238, v39, v39
	v_mul_f32_e32 v152, 0x41549a78, v151
	v_or_b32_e32 v156, 23, v156
	v_pk_add_f32 v[236:237], v[238:239], v[236:237] op_sel_hi:[0,1]
	v_mul_f32_e32 v238, v53, v53
	v_cmp_gt_f32_e32 vcc, s21, v152
	v_cvt_f32_ubyte0_e32 v156, v156
	v_pk_add_f32 v[236:237], v[238:239], v[236:237] op_sel_hi:[0,1]
	v_mul_f32_e32 v238, v231, v231
	v_cndmask_b32_e32 v152, 0, v252, vcc
	v_mul_f32_e32 v156, 0xbd000000, v156
	v_pk_add_f32 v[236:237], v[238:239], v[236:237] op_sel_hi:[0,1]
	v_mul_f32_e32 v238, v59, v59
	v_fmac_f32_e32 v152, 0x41549a78, v151
	v_mul_f32_e32 v158, 0x41549a78, v156
	v_pk_add_f32 v[236:237], v[238:239], v[236:237] op_sel_hi:[0,1]
	v_mul_f32_e32 v238, v49, v49
	v_exp_f32_e32 v151, v152
	v_sin_f32_e32 v153, v150
	v_cos_f32_e32 v152, v150
	v_cndmask_b32_e32 v150, 0, v250, vcc
	v_cmp_gt_f32_e32 vcc, s21, v158
	v_pk_add_f32 v[236:237], v[238:239], v[236:237] op_sel_hi:[0,1]
	v_mul_f32_e32 v238, v55, v55
	v_cndmask_b32_e32 v158, 0, v252, vcc
	v_pk_add_f32 v[236:237], v[238:239], v[236:237] op_sel_hi:[0,1]
	v_mul_f32_e32 v238, v61, v61
	v_fmac_f32_e32 v158, 0x41549a78, v156
	v_pk_add_f32 v[236:237], v[238:239], v[236:237] op_sel_hi:[0,1]
	v_mul_f32_e32 v238, v63, v63
	v_exp_f32_e32 v156, v158
	v_pk_add_f32 v[236:237], v[238:239], v[236:237] op_sel_hi:[0,1]
	v_mul_f32_e32 v238, v51, v51
	v_pk_add_f32 v[236:237], v[238:239], v[236:237] op_sel_hi:[0,1]
	v_mul_f32_e32 v238, v215, v215
	v_pk_add_f32 v[236:237], v[238:239], v[236:237] op_sel_hi:[0,1]
	v_mul_f32_e32 v238, v219, v219
	s_waitcnt vmcnt(0)
	v_mov_b32_e32 v163, v2
	v_cndmask_b32_e32 v2, 0, v250, vcc
	v_lshlrev_b32_e32 v209, 16, v68
	v_lshlrev_b32_e32 v208, 16, v64
	v_pk_add_f32 v[236:237], v[238:239], v[236:237] op_sel_hi:[0,1]
	v_ldexp_f32 v2, v156, v2
	v_and_b32_e32 v211, 0xffff0000, v68
	v_and_b32_e32 v210, 0xffff0000, v64
	v_pk_fma_f32 v[236:237], v[208:209], v[208:209], v[236:237]
	v_mul_f32_e32 v2, 0.15915494, v2
	v_lshlrev_b32_e32 v199, 16, v69
	v_lshlrev_b32_e32 v198, 16, v65
	v_pk_fma_f32 v[236:237], v[210:211], v[210:211], v[236:237]
	v_mov_b32_e32 v162, v94
	v_mul_f32_e32 v94, v2, v157
	v_and_b32_e32 v203, 0xffff0000, v69
	v_and_b32_e32 v202, 0xffff0000, v65
	v_pk_fma_f32 v[236:237], v[198:199], v[198:199], v[236:237]
	v_floor_f32_e32 v94, v94
	v_lshlrev_b32_e32 v189, 16, v70
	v_lshlrev_b32_e32 v188, 16, v66
	v_pk_fma_f32 v[236:237], v[202:203], v[202:203], v[236:237]
	v_ldexp_f32 v150, v151, v150
	v_fma_f32 v94, v2, v157, -v94
	v_and_b32_e32 v193, 0xffff0000, v70
	v_and_b32_e32 v192, 0xffff0000, v66
	v_pk_fma_f32 v[236:237], v[188:189], v[188:189], v[236:237]
	v_mul_f32_e32 v154, 0.15915494, v150
	v_sin_f32_e32 v159, v94
	v_cos_f32_e32 v158, v94
	v_mul_f32_e32 v94, v2, v164
	v_mov_b32_e32 v170, v88
	v_mov_b32_e32 v171, v4
	v_mov_b32_e32 v4, v89
	v_lshlrev_b32_e32 v89, 16, v71
	v_lshlrev_b32_e32 v88, 16, v67
	v_pk_fma_f32 v[236:237], v[192:193], v[192:193], v[236:237]
	v_mul_f32_e32 v150, v154, v157
	v_mul_f32_e32 v155, v154, v164
	v_floor_f32_e32 v94, v94
	v_and_b32_e32 v175, 0xffff0000, v71
	v_and_b32_e32 v174, 0xffff0000, v67
	v_pk_fma_f32 v[236:237], v[88:89], v[88:89], v[236:237]
	v_floor_f32_e32 v150, v150
	v_floor_f32_e32 v155, v155
	v_fma_f32 v2, v2, v164, -v94
	v_mov_b32_e32 v168, v90
	v_mov_b32_e32 v169, v6
	v_mov_b32_e32 v6, v91
	v_lshlrev_b32_e32 v91, 16, v84
	v_lshlrev_b32_e32 v90, 16, v80
	v_pk_fma_f32 v[236:237], v[174:175], v[174:175], v[236:237]
	v_fma_f32 v151, v154, v157, -v150
	v_fma_f32 v155, v154, v164, -v155
	v_lshlrev_b32_e32 v160, 16, v83
	v_sin_f32_e32 v157, v2
	v_cos_f32_e32 v156, v2
	v_and_b32_e32 v164, 0xffff0000, v83
	v_mov_b32_e32 v2, v95
	v_lshlrev_b32_e32 v95, 16, v86
	v_mov_b32_e32 v166, v92
	v_and_b32_e32 v83, 0xffff0000, v86
	v_lshlrev_b32_e32 v86, 16, v81
; __device__ __forceinline__ float bf2f(short v) { return __uint_as_float(((unsigned)(unsigned short)v) << 16); }
; template <bool BAND>
; __device__ __forceinline__ void attn_body(const u16* Qb, const u16* __restrict__ Kh, const u16* __restrict__ Vh, u16* Ob, int NT, int kpos0, int qpos0, float sink_l2, char* lds, const float* __restrict__ qn) {
;     ...
;       for (int e = 0; e < 8; ++e) { qf[d0][e] = bf2f(qr[d0][e]); ss += qf[d0][e] * qf[d0][e]; }
;     { auto rr = __builtin_amdgcn_permlane32_swap(__float_as_uint(ss), __float_as_uint(ss), false, false);
;       ss = __uint_as_float(rr[0]) + __uint_as_float(rr[1]); }
;     const float rs = rsqrtf(ss * (1.f / 128.f) + 1e-6f);
; #pragma unroll
;     for (int d0 = 0; d0 < 8; ++d0) {
;       const f32x4 g0 = *reinterpret_cast<const f32x4*>(qn + d0 * 16 + hi * 8), g1 = *reinterpret_cast<const f32x4*>(qn + d0 * 16 + hi * 8 + 4);
; #pragma unroll
;       for (int e = 0; e < 4; ++e) { qf[d0][e] *= rs * g0[e]; qf[d0][e + 4] *= rs * g1[e]; }
;     }
	v_and_b32_e32 v92, 0xffff0000, v81
	v_and_b32_e32 v81, 0xffff0000, v84
	v_and_b32_e32 v80, 0xffff0000, v80
	v_pk_fma_f32 v[236:237], v[90:91], v[90:91], v[236:237]
	v_lshlrev_b32_e32 v161, 16, v87
	v_and_b32_e32 v165, 0xffff0000, v87
	v_lshlrev_b32_e32 v87, 16, v85
	v_pk_fma_f32 v[236:237], v[80:81], v[80:81], v[236:237]
	v_mov_b32_e32 v167, v0
	v_mov_b32_e32 v0, v93
	v_and_b32_e32 v93, 0xffff0000, v85
	v_pk_fma_f32 v[236:237], v[86:87], v[86:87], v[236:237]
	v_lshlrev_b32_e32 v94, 16, v82
	v_pk_fma_f32 v[236:237], v[92:93], v[92:93], v[236:237]
	v_and_b32_e32 v82, 0xffff0000, v82
	v_pk_fma_f32 v[236:237], v[94:95], v[94:95], v[236:237]
	v_mul_f32_e32 v238, v209, v209
	v_pk_fma_f32 v[236:237], v[82:83], v[82:83], v[236:237]
	v_mov_b32_e32 v206, v93
	v_pk_fma_f32 v[236:237], v[160:161], v[160:161], v[236:237]
	v_mov_b32_e32 v207, v87
	v_pk_fma_f32 v[236:237], v[164:165], v[164:165], v[236:237]
	v_mov_b32_e32 v194, v83
	v_pk_add_f32 v[236:237], v[238:239], v[236:237] op_sel_hi:[0,1]
	v_mul_f32_e32 v238, v211, v211
	v_pk_add_f32 v[236:237], v[238:239], v[236:237] op_sel_hi:[0,1]
	v_mul_f32_e32 v238, v199, v199
	v_pk_add_f32 v[236:237], v[238:239], v[236:237] op_sel_hi:[0,1]
	v_mul_f32_e32 v238, v203, v203
	v_pk_add_f32 v[236:237], v[238:239], v[236:237] op_sel_hi:[0,1]
	v_mul_f32_e32 v238, v189, v189
	v_pk_add_f32 v[236:237], v[238:239], v[236:237] op_sel_hi:[0,1]
	v_mul_f32_e32 v238, v193, v193
	v_pk_add_f32 v[236:237], v[238:239], v[236:237] op_sel_hi:[0,1]
	v_mul_f32_e32 v238, v89, v89
	v_pk_add_f32 v[236:237], v[238:239], v[236:237] op_sel_hi:[0,1]
	v_mul_f32_e32 v238, v175, v175
	v_pk_add_f32 v[236:237], v[238:239], v[236:237] op_sel_hi:[0,1]
	v_mul_f32_e32 v238, v91, v91
	v_pk_add_f32 v[236:237], v[238:239], v[236:237] op_sel_hi:[0,1]
	v_mul_f32_e32 v238, v81, v81
	v_pk_add_f32 v[236:237], v[238:239], v[236:237] op_sel_hi:[0,1]
	v_mul_f32_e32 v238, v87, v87
	v_pk_add_f32 v[236:237], v[238:239], v[236:237] op_sel_hi:[0,1]
	v_mov_b32_e32 v239, v30
	v_pk_fma_f32 v[206:207], v[206:207], v[206:207], v[236:237]
	v_mul_f32_e32 v30, v95, v95
	v_mov_b32_e32 v195, v95
	v_pk_add_f32 v[206:207], v[30:31], v[206:207] op_sel_hi:[0,1]
	v_pk_fma_f32 v[194:195], v[194:195], v[194:195], v[206:207]
	v_mul_f32_e32 v30, v161, v161
	v_mov_b32_e32 v182, v165
	v_mov_b32_e32 v183, v161
	v_pk_add_f32 v[194:195], v[30:31], v[194:195] op_sel_hi:[0,1]
	v_pk_fma_f32 v[182:183], v[182:183], v[182:183], v[194:195]
	s_mov_b32 s21, 0x800000
	v_mov_b32_e32 v30, v182
	s_nop 1
	v_permlane32_swap_b32_e32 v182, v30
	v_add_f32_e32 v30, v182, v30
	v_fmamk_f32 v30, v30, 0x3c000000, v229
	v_mov_b32_e32 v238, v34
	v_mul_f32_e32 v34, 0x4b800000, v30
	v_cmp_gt_f32_e32 vcc, s21, v30
	v_mov_b32_e32 v178, v78
	v_mov_b32_e32 v179, v10
	v_cndmask_b32_e32 v30, v30, v34, vcc
	v_rsq_f32_e32 v177, v30
	v_mov_b32_e32 v30, v35
	v_mov_b32_e32 v35, v28
	v_mov_b32_e32 v34, v32
	v_mul_f32_e32 v28, 0x45800000, v177
	v_cndmask_b32_e32 v32, v177, v28, vcc
	v_mov_b32_e32 v28, v33
	v_pk_mul_f32 v[24:25], v[24:25], v[32:33] op_sel_hi:[1,0]
	v_pk_mul_f32 v[28:29], v[28:29], v[32:33] op_sel_hi:[1,0]
	v_pk_mul_f32 v[24:25], v[24:25], v[38:39]
	v_pk_mul_f32 v[38:39], v[238:239], v[32:33] op_sel_hi:[1,0]
	v_pk_mul_f32 v[30:31], v[30:31], v[32:33] op_sel_hi:[1,0]
	v_pk_mul_f32 v[20:21], v[20:21], v[32:33] op_sel_hi:[1,0]
	v_mov_b32_e32 v10, v79
	v_mov_b32_e32 v196, v76
	v_mov_b32_e32 v197, v8
	v_mov_b32_e32 v8, v77
	v_mov_b32_e32 v204, v74
	v_mov_b32_e32 v205, v14
	v_mov_b32_e32 v14, v75
	v_mov_b32_e32 v212, v72
	v_mov_b32_e32 v213, v12
	v_mov_b32_e32 v12, v73
	v_pk_mul_f32 v[34:35], v[34:35], v[32:33] op_sel_hi:[1,0]
	v_pk_mul_f32 v[28:29], v[28:29], v[40:41]
	v_pk_mul_f32 v[38:39], v[38:39], v[42:43]
	v_pk_mul_f32 v[40:41], v[56:57], v[32:33] op_sel_hi:[1,0]
	v_pk_mul_f32 v[30:31], v[30:31], v[44:45]
	v_pk_mul_f32 v[42:43], v[226:227], v[32:33] op_sel_hi:[1,0]
	v_pk_mul_f32 v[44:45], v[220:221], v[32:33] op_sel_hi:[1,0]
	v_pk_mul_f32 v[20:21], v[20:21], v[48:49]
	v_pk_mul_f32 v[16:17], v[16:17], v[32:33] op_sel_hi:[1,0]
	v_pk_mul_f32 v[48:49], v[222:223], v[32:33] op_sel_hi:[1,0]
	v_pk_mul_f32 v[22:23], v[22:23], v[32:33] op_sel_hi:[1,0]
	v_pk_mul_f32 v[4:5], v[32:33], v[4:5] op_sel_hi:[0,1]
	v_pk_mul_f32 v[0:1], v[32:33], v[0:1] op_sel_hi:[0,1]
	v_pk_mul_f32 v[34:35], v[34:35], v[234:235]
	v_pk_mul_f32 v[182:183], v[232:233], v[32:33] op_sel_hi:[1,0]
	v_pk_mul_f32 v[40:41], v[40:41], v[52:53]
	v_pk_mul_f32 v[26:27], v[26:27], v[32:33] op_sel_hi:[1,0]
	v_pk_mul_f32 v[42:43], v[42:43], v[58:59]
	v_pk_mul_f32 v[44:45], v[44:45], v[62:63]
	v_pk_mul_f32 v[16:17], v[16:17], v[50:51]
	v_pk_mul_f32 v[48:49], v[48:49], v[54:55]
	v_pk_mul_f32 v[50:51], v[216:217], v[32:33] op_sel_hi:[1,0]
	v_pk_mul_f32 v[22:23], v[22:23], v[60:61]
	v_pk_mul_f32 v[18:19], v[18:19], v[32:33] op_sel_hi:[1,0]
	v_pk_mul_f32 v[52:53], v[32:33], v[212:213] op_sel_hi:[0,1]
	v_pk_mul_f32 v[54:55], v[32:33], v[196:197] op_sel_hi:[0,1]
	v_pk_mul_f32 v[12:13], v[32:33], v[12:13] op_sel_hi:[0,1]
	v_pk_mul_f32 v[8:9], v[32:33], v[8:9] op_sel_hi:[0,1]
	v_pk_mul_f32 v[56:57], v[32:33], v[204:205] op_sel_hi:[0,1]
	v_pk_mul_f32 v[58:59], v[32:33], v[178:179] op_sel_hi:[0,1]
	v_pk_mul_f32 v[14:15], v[32:33], v[14:15] op_sel_hi:[0,1]
	v_pk_mul_f32 v[10:11], v[32:33], v[10:11] op_sel_hi:[0,1]
	v_pk_mul_f32 v[60:61], v[32:33], v[170:171] op_sel_hi:[0,1]
	v_pk_mul_f32 v[62:63], v[32:33], v[166:167] op_sel_hi:[0,1]
	v_pk_mul_f32 v[4:5], v[4:5], v[80:81]
	v_pk_mul_f32 v[0:1], v[0:1], v[82:83]
	v_pk_mul_f32 v[80:81], v[32:33], v[168:169] op_sel_hi:[0,1]
	v_pk_mul_f32 v[82:83], v[32:33], v[162:163] op_sel_hi:[0,1]
	v_pk_mul_f32 v[6:7], v[32:33], v[6:7] op_sel_hi:[0,1]
; template <bool BAND>
; __device__ __forceinline__ void attn_body(const u16* Qb, const u16* __restrict__ Kh, const u16* __restrict__ Vh, u16* Ob, int NT, int kpos0, int qpos0, float sink_l2, char* lds, const float* __restrict__ qn) {
;     ...
;       const float prow = (float)(pos >> 6), pcol = (float)(pos & 63);
; #pragma unroll
;       for (int dp = 0; dp < 2; ++dp)
; #pragma unroll
;         for (int e = 0; e < 8; ++e) {
;           const float frv = exp2f(-(float)(dp * 16 + hi * 8 + e) * (1.f / 32.f) * 13.287712379549449f) * 0.15915494309189535f;
;           float r = prow * frv; r = r - floorf(r);
;           float sn = __builtin_amdgcn_sinf(r), cs = __builtin_amdgcn_cosf(r);
;           float x1 = qf[dp][e], x2 = qf[dp + 2][e];
;           qf[dp][e] = x1 * cs - x2 * sn; qf[dp + 2][e] = x2 * cs + x1 * sn;
;           r = pcol * frv; r = r - floorf(r);
;           sn = __builtin_amdgcn_sinf(r); cs = __builtin_amdgcn_cosf(r);
;           x1 = qf[4 + dp][e]; x2 = qf[6 + dp][e];
;           qf[4 + dp][e] = x1 * cs - x2 * sn; qf[6 + dp][e] = x2 * cs + x1 * sn;
;         }
	v_pk_mul_f32 v[2:3], v[32:33], v[2:3] op_sel_hi:[0,1]
	v_mov_b32_e32 v32, v97
	v_mov_b32_e32 v33, v96
	v_pk_mul_f32 v[32:33], v[32:33], v[34:35]
	v_pk_mul_f32 v[52:53], v[52:53], v[208:209]
	v_pk_mul_f32 v[80:81], v[80:81], v[86:87]
	v_sub_f32_e32 v86, v32, v33
	v_pk_mul_f32 v[32:33], v[96:97], v[34:35]
	v_sin_f32_e32 v102, v103
	v_add_f32_e32 v34, v32, v33
	v_pk_mul_f32 v[32:33], v[200:201], v[52:53]
	v_cos_f32_e32 v103, v103
	v_sub_f32_e32 v35, v32, v33
	v_pk_mul_f32 v[32:33], v[98:99], v[52:53]
	v_sin_f32_e32 v106, v107
	v_add_f32_e32 v52, v32, v33
	v_pk_mul_f32 v[32:33], v[100:101], v[28:29]
	v_cos_f32_e32 v107, v107
	v_sub_f32_e32 v53, v32, v33
	v_mov_b32_e32 v32, v101
	v_mov_b32_e32 v33, v100
	v_mov_b32_e32 v190, v105
	v_mov_b32_e32 v191, v104
	v_pk_mul_f32 v[12:13], v[12:13], v[210:211]
	v_pk_mul_f32 v[28:29], v[32:33], v[28:29]
	v_sin_f32_e32 v109, v108
	v_add_f32_e32 v32, v28, v29
	v_pk_mul_f32 v[28:29], v[104:105], v[12:13]
	v_pk_mul_f32 v[12:13], v[190:191], v[12:13]
	v_sub_f32_e32 v28, v28, v29
	v_add_f32_e32 v29, v12, v13
	v_mov_b32_e32 v12, v103
	v_mov_b32_e32 v13, v102
	v_cos_f32_e32 v108, v108
	v_pk_mul_f32 v[12:13], v[12:13], v[38:39]
	v_mov_b32_e32 v186, v107
	v_mov_b32_e32 v187, v106
	v_pk_mul_f32 v[56:57], v[56:57], v[198:199]
	v_sub_f32_e32 v33, v12, v13
	v_pk_mul_f32 v[12:13], v[102:103], v[38:39]
	v_sin_f32_e32 v110, v111
	v_add_f32_e32 v38, v12, v13
	v_pk_mul_f32 v[12:13], v[186:187], v[56:57]
	v_cos_f32_e32 v111, v111
	v_sub_f32_e32 v39, v12, v13
	v_pk_mul_f32 v[12:13], v[106:107], v[56:57]
	v_pk_mul_f32 v[14:15], v[14:15], v[202:203]
	v_add_f32_e32 v56, v12, v13
	v_pk_mul_f32 v[12:13], v[108:109], v[30:31]
	v_sin_f32_e32 v114, v115
	v_sub_f32_e32 v57, v12, v13
	v_mov_b32_e32 v12, v109
	v_mov_b32_e32 v13, v108
	v_pk_mul_f32 v[12:13], v[12:13], v[30:31]
	v_cos_f32_e32 v115, v115
	v_mov_b32_e32 v184, v113
	v_mov_b32_e32 v185, v112
	v_add_f32_e32 v30, v12, v13
	v_pk_mul_f32 v[12:13], v[112:113], v[14:15]
	v_pk_mul_f32 v[46:47], v[182:183], v[46:47]
	v_sub_f32_e32 v31, v12, v13
	v_pk_mul_f32 v[12:13], v[184:185], v[14:15]
	v_sin_f32_e32 v117, v116
	v_add_f32_e32 v14, v12, v13
	v_mov_b32_e32 v12, v111
	v_mov_b32_e32 v13, v110
	v_cos_f32_e32 v116, v116
	v_pk_mul_f32 v[12:13], v[12:13], v[46:47]
	v_mov_b32_e32 v172, v115
	v_mov_b32_e32 v173, v114
	v_pk_mul_f32 v[54:55], v[54:55], v[188:189]
	v_sub_f32_e32 v15, v12, v13
	v_pk_mul_f32 v[12:13], v[110:111], v[46:47]
	v_sin_f32_e32 v118, v119
	v_add_f32_e32 v46, v12, v13
	v_pk_mul_f32 v[12:13], v[172:173], v[54:55]
	v_cos_f32_e32 v119, v119
	v_sub_f32_e32 v47, v12, v13
	v_pk_mul_f32 v[12:13], v[114:115], v[54:55]
	v_sin_f32_e32 v122, v123
	v_add_f32_e32 v54, v12, v13
	v_pk_mul_f32 v[12:13], v[116:117], v[24:25]
	v_cos_f32_e32 v123, v123
	v_sub_f32_e32 v55, v12, v13
	v_mov_b32_e32 v12, v117
	v_mov_b32_e32 v13, v116
	v_mov_b32_e32 v84, v121
	v_mov_b32_e32 v85, v120
	v_pk_mul_f32 v[8:9], v[8:9], v[192:193]
	v_pk_mul_f32 v[12:13], v[12:13], v[24:25]
	v_sin_f32_e32 v125, v124
	v_add_f32_e32 v24, v12, v13
	v_pk_mul_f32 v[12:13], v[120:121], v[8:9]
	v_pk_mul_f32 v[8:9], v[84:85], v[8:9]
	v_sub_f32_e32 v12, v12, v13
	v_add_f32_e32 v13, v8, v9
	v_mov_b32_e32 v8, v119
	v_mov_b32_e32 v9, v118
	v_cos_f32_e32 v124, v124
	v_pk_mul_f32 v[8:9], v[8:9], v[40:41]
	v_mov_b32_e32 v78, v123
	v_mov_b32_e32 v79, v122
	v_pk_mul_f32 v[58:59], v[58:59], v[88:89]
	v_sub_f32_e32 v25, v8, v9
	v_pk_mul_f32 v[8:9], v[118:119], v[40:41]
	v_pk_mul_f32 v[26:27], v[26:27], v[230:231]
	v_add_f32_e32 v40, v8, v9
	v_pk_mul_f32 v[8:9], v[78:79], v[58:59]
	v_sin_f32_e32 v126, v127
	v_sub_f32_e32 v41, v8, v9
	v_pk_mul_f32 v[8:9], v[122:123], v[58:59]
	v_cos_f32_e32 v127, v127
	v_add_f32_e32 v58, v8, v9
	v_pk_mul_f32 v[8:9], v[124:125], v[26:27]
	v_pk_mul_f32 v[10:11], v[10:11], v[174:175]
	v_sub_f32_e32 v59, v8, v9
	v_mov_b32_e32 v8, v125
	v_mov_b32_e32 v9, v124
	v_pk_mul_f32 v[8:9], v[8:9], v[26:27]
	v_sin_f32_e32 v130, v131
	v_cos_f32_e32 v131, v131
	v_mov_b32_e32 v76, v129
	v_mov_b32_e32 v77, v128
	v_add_f32_e32 v26, v8, v9
	v_pk_mul_f32 v[8:9], v[128:129], v[10:11]
	v_sin_f32_e32 v133, v132
	v_sub_f32_e32 v27, v8, v9
	v_pk_mul_f32 v[8:9], v[76:77], v[10:11]
	v_cos_f32_e32 v132, v132
	v_add_f32_e32 v10, v8, v9
	v_mov_b32_e32 v8, v127
	v_mov_b32_e32 v9, v126
	v_pk_mul_f32 v[8:9], v[8:9], v[42:43]
	v_mov_b32_e32 v74, v131
	v_mov_b32_e32 v75, v130
	v_pk_mul_f32 v[60:61], v[60:61], v[90:91]
	v_sub_f32_e32 v11, v8, v9
	v_pk_mul_f32 v[8:9], v[126:127], v[42:43]
	v_sin_f32_e32 v134, v135
	v_add_f32_e32 v42, v8, v9
	v_pk_mul_f32 v[8:9], v[74:75], v[60:61]
	v_cos_f32_e32 v135, v135
	v_sub_f32_e32 v43, v8, v9
	v_pk_mul_f32 v[8:9], v[130:131], v[60:61]
	v_sin_f32_e32 v138, v139
	v_add_f32_e32 v60, v8, v9
	v_pk_mul_f32 v[8:9], v[132:133], v[20:21]
	v_cos_f32_e32 v139, v139
	v_sub_f32_e32 v61, v8, v9
	v_mov_b32_e32 v8, v133
	v_mov_b32_e32 v9, v132
	v_mov_b32_e32 v72, v137
	v_mov_b32_e32 v73, v136
	v_pk_mul_f32 v[8:9], v[8:9], v[20:21]
	v_sin_f32_e32 v141, v140
	v_add_f32_e32 v20, v8, v9
	v_pk_mul_f32 v[8:9], v[136:137], v[4:5]
	v_pk_mul_f32 v[4:5], v[72:73], v[4:5]
	v_sub_f32_e32 v8, v8, v9
	v_add_f32_e32 v9, v4, v5
	v_mov_b32_e32 v4, v135
	v_mov_b32_e32 v5, v134
	v_cos_f32_e32 v140, v140
	v_pk_mul_f32 v[4:5], v[4:5], v[48:49]
	v_mov_b32_e32 v70, v139
	v_mov_b32_e32 v71, v138
	v_sub_f32_e32 v21, v4, v5
	v_pk_mul_f32 v[4:5], v[134:135], v[48:49]
	v_sin_f32_e32 v142, v143
	v_add_f32_e32 v48, v4, v5
	v_pk_mul_f32 v[4:5], v[70:71], v[80:81]
	v_cos_f32_e32 v143, v143
	v_sub_f32_e32 v49, v4, v5
	v_pk_mul_f32 v[4:5], v[138:139], v[80:81]
	v_pk_mul_f32 v[6:7], v[6:7], v[92:93]
	v_add_f32_e32 v70, v4, v5
	v_pk_mul_f32 v[4:5], v[140:141], v[22:23]
; __device__ __forceinline__ int v_st(int k, int c) { const int kk = (k & ~0xC) | ((k & 4) << 1) | ((k & 8) >> 1); return ((kk >> 3) * 4 + (c >> 5)) * 512 + ((kk & 7) * 32 + (c & 31)) * 2; }
; __device__ __forceinline__ int v_rd_base(int lane) { return ((lane & 3) << 3) | (((lane >> 2) & 3) << 6) | (((lane >> 4) & 1) << 5) | (((lane >> 5) & 1) << 8); }
; #define SLOAD(i, k0) do { sr_[i].vs0 = *reinterpret_cast<const bf16x8*>(&Vh[(long)((k0) + sr) * LDK + sc]); sr_[i].vs1 = *reinterpret_cast<const bf16x8*>(&Vh[(long)((k0) + 32 + sr) * LDK + sc]); \
;     sr_[i].ks0 = *reinterpret_cast<const bf16x8*>(&Kh[(long)((k0) + sr) * LDK + sc]); sr_[i].ks1 = *reinterpret_cast<const bf16x8*>(&Kh[(long)((k0) + 32 + sr) * LDK + sc]); } while (0)
; #define SWRITE(b, i) do { *(bf16x8*)((char*)V_lds + (b) * SHM_V + vst0) = sr_[i].vs0;          \
;     *(bf16x8*)((char*)V_lds + (b) * SHM_V + vst1) = sr_[i].vs1; int kc = sc * 2;               \
;     *(bf16x8*)((char*)K_lds + (b) * SHM_K + KSWZ(sr, kc)) = sr_[i].ks0;                       \
;     *(bf16x8*)((char*)K_lds + (b) * SHM_K + KSWZ(32 + sr, kc)) = sr_[i].ks1; } while (0)
; template <bool BAND>
; __device__ __forceinline__ void attn_body(const u16* Qb, const u16* __restrict__ Kh, const u16* __restrict__ Vh, u16* Ob, int NT, int kpos0, int qpos0, float sink_l2, char* lds, const float* __restrict__ qn) {
;     ...
;     for (int d0 = 0; d0 < 8; ++d0) qr[d0] = pack8(qf[d0]);
;   }
;   const int sr = tid >> 4, sc = (tid & 15) * 8, vst0 = v_st(sr, sc), vst1 = v_st(32 + sr, sc);
;   const int vb0 = (int)(uintptr_t)V_lds + v_rd_base(lane);
;   const int dq = kpos0 + 4 * hi - (qpos0 + wid * QBLK + r32);
;   struct { bf16x8 vs0, vs1, ks0, ks1; } sr_[SDEPTH];
;     ...
;   f32x16 pA0, pA1, pB0, pB1; float mnA, mnB, alA, alB; bf16x8 pa0, pa1, pa2, pa3;
;   constexpr int SE = 0, SO = SDEPTH - 1;
;   SLOAD(SE, 0); asm volatile("s_waitcnt vmcnt(0)" ::: "memory"); SWRITE(0, SE); __syncthreads();
	v_sin_f32_e32 v146, v147
	v_sub_f32_e32 v71, v4, v5
	v_mov_b32_e32 v4, v141
	v_mov_b32_e32 v5, v140
	v_pk_mul_f32 v[4:5], v[4:5], v[22:23]
	v_cos_f32_e32 v147, v147
	v_mov_b32_e32 v68, v145
	v_mov_b32_e32 v69, v144
	v_add_f32_e32 v22, v4, v5
	v_pk_mul_f32 v[4:5], v[144:145], v[6:7]
	v_sin_f32_e32 v149, v148
	v_sub_f32_e32 v23, v4, v5
	v_pk_mul_f32 v[4:5], v[68:69], v[6:7]
	v_cos_f32_e32 v148, v148
	v_add_f32_e32 v6, v4, v5
	v_mov_b32_e32 v4, v143
	v_mov_b32_e32 v5, v142
	v_pk_mul_f32 v[4:5], v[4:5], v[44:45]
	v_mov_b32_e32 v66, v147
	v_mov_b32_e32 v67, v146
	v_pk_mul_f32 v[62:63], v[62:63], v[94:95]
	v_sub_f32_e32 v7, v4, v5
	v_pk_mul_f32 v[4:5], v[142:143], v[44:45]
	v_sin_f32_e32 v150, v151
	v_add_f32_e32 v44, v4, v5
	v_pk_mul_f32 v[4:5], v[66:67], v[62:63]
	v_cos_f32_e32 v151, v151
	v_sub_f32_e32 v45, v4, v5
	v_pk_mul_f32 v[4:5], v[146:147], v[62:63]
	v_sin_f32_e32 v154, v155
	v_add_f32_e32 v62, v4, v5
	v_pk_mul_f32 v[4:5], v[148:149], v[16:17]
	v_cos_f32_e32 v155, v155
	v_sub_f32_e32 v63, v4, v5
	v_mov_b32_e32 v4, v149
	v_mov_b32_e32 v5, v148
	v_mov_b32_e32 v64, v153
	v_mov_b32_e32 v65, v152
	v_pk_mul_f32 v[4:5], v[4:5], v[16:17]
	v_pk_mul_f32 v[50:51], v[50:51], v[214:215]
	v_add_f32_e32 v16, v4, v5
	v_pk_mul_f32 v[4:5], v[152:153], v[0:1]
	v_pk_mul_f32 v[0:1], v[64:65], v[0:1]
	v_sub_f32_e32 v4, v4, v5
	v_add_f32_e32 v5, v0, v1
	v_mov_b32_e32 v0, v151
	v_mov_b32_e32 v1, v150
	v_pk_mul_f32 v[0:1], v[0:1], v[50:51]
	v_mov_b32_e32 v36, v155
	v_mov_b32_e32 v37, v154
	v_pk_mul_f32 v[82:83], v[82:83], v[160:161]
	v_sub_f32_e32 v17, v0, v1
	v_pk_mul_f32 v[0:1], v[150:151], v[50:51]
	v_pk_mul_f32 v[18:19], v[18:19], v[218:219]
	v_add_f32_e32 v50, v0, v1
	v_pk_mul_f32 v[0:1], v[36:37], v[82:83]
	v_pk_mul_f32 v[2:3], v[2:3], v[164:165]
	v_sub_f32_e32 v36, v0, v1
	v_pk_mul_f32 v[0:1], v[154:155], v[82:83]
	v_cvt_pk_bf16_f32 v124, v86, v53
	v_cvt_pk_bf16_f32 v125, v33, v57
	v_cvt_pk_bf16_f32 v126, v15, v55
	v_cvt_pk_bf16_f32 v127, v25, v59
	v_cvt_pk_bf16_f32 v120, v11, v61
	s_nop 0
	v_add_f32_e32 v37, v0, v1
	v_pk_mul_f32 v[0:1], v[158:159], v[18:19]
	v_cvt_pk_bf16_f32 v121, v21, v71
	v_cvt_pk_bf16_f32 v122, v7, v63
	s_add_i32 s21, 32, 0x10000
	v_sub_f32_e32 v51, v0, v1
	v_mov_b32_e32 v0, v159
	v_mov_b32_e32 v1, v158
	v_pk_mul_f32 v[0:1], v[0:1], v[18:19]
	v_cvt_pk_bf16_f32 v123, v17, v51
	v_cvt_pk_bf16_f32 v116, v34, v32
	v_cvt_pk_bf16_f32 v117, v38, v30
	v_cvt_pk_bf16_f32 v118, v46, v24
	v_cvt_pk_bf16_f32 v119, v40, v26
	s_nop 0
	v_add_f32_e32 v18, v0, v1
	v_pk_mul_f32 v[0:1], v[156:157], v[2:3]
	v_cvt_pk_bf16_f32 v112, v42, v20
	v_cvt_pk_bf16_f32 v113, v48, v22
	v_cvt_pk_bf16_f32 v114, v44, v16
	v_cvt_pk_bf16_f32 v115, v50, v18
	v_ashrrev_i32_e32 v48, 4, v247
	v_sub_f32_e32 v19, v0, v1
	v_mov_b32_e32 v0, v157
	v_mov_b32_e32 v1, v156
	v_pk_mul_f32 v[0:1], v[0:1], v[2:3]
	v_lshlrev_b32_e32 v18, 3, v247
	v_add_f32_e32 v0, v0, v1
	v_cvt_pk_bf16_f32 v108, v35, v28
	v_cvt_pk_bf16_f32 v109, v39, v31
	v_cvt_pk_bf16_f32 v110, v47, v12
	v_cvt_pk_bf16_f32 v111, v41, v27
	v_cvt_pk_bf16_f32 v104, v43, v8
	v_cvt_pk_bf16_f32 v105, v49, v23
	v_cvt_pk_bf16_f32 v106, v45, v4
	v_cvt_pk_bf16_f32 v107, v36, v19
	v_cvt_pk_bf16_f32 v100, v52, v29
	v_cvt_pk_bf16_f32 v101, v56, v14
	v_cvt_pk_bf16_f32 v102, v54, v13
	v_cvt_pk_bf16_f32 v103, v58, v10
	v_cvt_pk_bf16_f32 v96, v60, v9
	v_cvt_pk_bf16_f32 v97, v70, v6
	v_cvt_pk_bf16_f32 v98, v62, v5
	v_cvt_pk_bf16_f32 v99, v37, v0
	v_and_b32_e32 v0, 0x78, v18
	v_ashrrev_i32_e32 v49, 31, v48
	v_lshlrev_b32_e32 v19, 1, v0
	v_lshlrev_b64 v[50:51], 9, v[48:49]
	v_or_b32_e32 v50, v50, v19
	v_lshl_add_u64 v[0:1], s[6:7], 0, v[50:51]
	v_add_u32_e32 v16, 32, v48
	global_load_dwordx4 v[0:3], v[0:1], off
	v_ashrrev_i32_e32 v17, 31, v16
	v_lshlrev_b64 v[12:13], 9, v[16:17]
	v_or_b32_e32 v12, v12, v19
	v_lshl_add_u64 v[4:5], s[6:7], 0, v[12:13]
	v_lshl_add_u64 v[8:9], s[18:19], 0, v[50:51]
	v_lshl_add_u64 v[12:13], s[18:19], 0, v[12:13]
	global_load_dwordx4 v[4:7], v[4:5], off
	v_and_b32_e32 v17, 0xfffff0, v48
	global_load_dwordx4 v[8:11], v[8:9], off
	v_lshlrev_b32_e32 v20, 1, v48
	global_load_dwordx4 v[12:15], v[12:13], off
	v_and_or_b32 v17, v20, 8, v17
	v_lshrrev_b32_e32 v20, 1, v48
	v_lshrrev_b32_e32 v17, 1, v17
	v_bfe_u32 v18, v18, 5, 2
	v_and_b32_e32 v21, 3, v48
	v_or_b32_e32 v17, v17, v18
	v_and_or_b32 v20, v20, 4, v21
	v_lshlrev_b32_e32 v17, 9, v17
	v_lshlrev_b32_e32 v20, 6, v20
	v_and_b32_e32 v21, 48, v19
	v_or3_b32 v17, v17, v20, v21
	v_and_b32_e32 v22, 0xfffff0, v16
	v_lshlrev_b32_e32 v23, 1, v16
	v_and_or_b32 v22, v23, 8, v22
	v_add_u32_e32 v185, 32, v17
	v_lshrrev_b32_e32 v22, 1, v22
	s_waitcnt vmcnt(0)
	v_or_b32_e32 v18, v22, v18
	v_lshlrev_b32_e32 v18, 9, v18
	v_or3_b32 v18, v18, v20, v21
	v_lshlrev_b32_e32 v52, 4, v247
	v_add_u32_e32 v186, 32, v18
	s_mov_b64 s[26:27], 0x8000
	v_and_b32_e32 v74, 63, v247
	v_readlane_b32 s36, v253, 15
	v_readlane_b32 s37, v253, 16
	s_mov_b32 s53, s37
	v_readlane_b32 s38, v253, 17
	v_readlane_b32 s39, v253, 18
	v_readlane_b32 s40, v253, 19
	v_readlane_b32 s41, v253, 20
	v_readlane_b32 s42, v253, 21
	v_readlane_b32 s43, v253, 22
	v_readlane_b32 s44, v253, 23
	v_readlane_b32 s45, v253, 24
	v_readlane_b32 s46, v253, 25
	v_readlane_b32 s47, v253, 26
	v_readlane_b32 s48, v253, 27
	v_readlane_b32 s49, v253, 28
	v_readlane_b32 s50, v253, 29
	v_readlane_b32 s51, v253, 30
	v_writelane_b32 v253, s52, 15
	s_cmp_lg_u32 32, -1
	s_cselect_b32 s25, 32, 0
	s_add_i32 s22, s23, -1
	s_add_i32 s23, s23, -3
	v_writelane_b32 v253, s53, 16
	v_writelane_b32 v253, s54, 17
	v_writelane_b32 v253, s55, 18
	v_writelane_b32 v253, s56, 19
	v_writelane_b32 v253, s57, 20
	v_writelane_b32 v253, s58, 21
	v_writelane_b32 v253, s59, 22
	v_writelane_b32 v253, s60, 23
	v_writelane_b32 v253, s61, 24
	v_writelane_b32 v253, s62, 25
	s_mov_b32 s36, s37
	v_writelane_b32 v253, s63, 26
	s_mov_b32 s38, s37
	s_mov_b32 s39, s37
	s_mov_b32 s40, s37
	s_mov_b32 s41, s37
	s_mov_b32 s42, s37
	s_mov_b32 s43, s37
	s_mov_b32 s44, s37
	s_mov_b32 s45, s37
	s_mov_b32 s46, s37
	s_mov_b32 s47, s37
	s_waitcnt vmcnt(3)
	ds_write_b128 v185, v[0:3]
	v_lshlrev_b32_e32 v0, 8, v48
	v_and_b32_e32 v1, 0x70, v247
	v_bitop3_b32 v0, v19, v0, v1 bitop3:0xde
	v_add_u32_e32 v187, 32, v0
	v_lshlrev_b32_e32 v0, 8, v16
	v_bitop3_b32 v0, v19, v0, v1 bitop3:0xde
	v_add_u32_e32 v188, 32, v0
	s_waitcnt vmcnt(2)
	ds_write_b128 v186, v[4:7]
	s_waitcnt vmcnt(1)
	ds_write_b128 v187, v[8:11] offset:32768
	s_mov_b32 s48, s37
	s_waitcnt vmcnt(0)
	ds_write_b128 v188, v[12:15] offset:32768
	v_lshlrev_b32_e32 v12, 8, v246
	v_and_b32_e32 v13, 0x70, v52
	v_bitop3_b32 v0, v180, v12, v13 bitop3:0xde
	v_add_u32_e32 v189, 32, v0
	s_waitcnt lgkmcnt(0)
	s_barrier
; #define SLOAD(i, k0) do { sr_[i].vs0 = *reinterpret_cast<const bf16x8*>(&Vh[(long)((k0) + sr) * LDK + sc]); sr_[i].vs1 = *reinterpret_cast<const bf16x8*>(&Vh[(long)((k0) + 32 + sr) * LDK + sc]); \
;     sr_[i].ks0 = *reinterpret_cast<const bf16x8*>(&Kh[(long)((k0) + sr) * LDK + sc]); sr_[i].ks1 = *reinterpret_cast<const bf16x8*>(&Kh[(long)((k0) + 32 + sr) * LDK + sc]); } while (0)
; __device__ __forceinline__ void qkt(f32x16& p0, f32x16& p1, const u16* Ks, const bf16x8* qr, int r32, int hi) {
;   p0 = f32x16{}; p1 = f32x16{};
; #pragma unroll
;   for (int d0 = 0; d0 < 8; ++d0) { int cb = (d0 * 16 + hi * 8) * 2;
;     bf16x8 b0 = *reinterpret_cast<const bf16x8*>((const char*)Ks + KSWZ(r32, cb));
;     bf16x8 b1 = *reinterpret_cast<const bf16x8*>((const char*)Ks + KSWZ(32 + r32, cb));
;     p0 = __builtin_amdgcn_mfma_f32_32x32x16_bf16(b0, qr[d0], p0, 0, 0, 0);
;     p1 = __builtin_amdgcn_mfma_f32_32x32x16_bf16(b1, qr[d0], p1, 0, 0, 0); }
; }
; template <bool BAND>
; __device__ __forceinline__ void attn_body(const u16* Qb, const u16* __restrict__ Kh, const u16* __restrict__ Vh, u16* Ob, int NT, int kpos0, int qpos0, float sink_l2, char* lds, const float* __restrict__ qn) {
;     ...
;   qkt(pA0, pA1, K_lds, qr, r32, hi); partialSM<BAND>(pA0, pA1, m_reg, mnA, alA, dq);
;   SLOAD(SO, KVBLK); if constexpr (SDEPTH == 2) { if (2 < NT) SLOAD(SE, 2 * KVBLK); }
	ds_read_b128 v[0:3], v189 offset:32768
	ds_read_b128 v[4:7], v189 offset:40960
	s_waitcnt lgkmcnt(1)
	v_mfma_f32_32x32x16_bf16 v[16:31], v[0:3], v[124:127], 0
	v_or_b32_e32 v0, 32, v180
	v_bitop3_b32 v0, v0, v12, v13 bitop3:0xde
	v_add_u32_e32 v192, 32, v0
	v_and_b32_e32 v15, 0xc0, v52
	v_lshlrev_b32_e32 v14, 3, v74
	s_mov_b32 s49, s37
	s_mov_b32 s50, s37
	s_waitcnt lgkmcnt(0)
	v_mfma_f32_32x32x16_bf16 v[32:47], v[4:7], v[124:127], 0
	ds_read_b128 v[0:3], v192 offset:32768
	ds_read_b128 v[4:7], v192 offset:40960
	s_mov_b32 s51, s37
	v_writelane_b32 v253, s64, 27
	v_writelane_b32 v253, s65, 28
	v_writelane_b32 v253, s66, 29
	v_writelane_b32 v253, s67, 30
	s_waitcnt lgkmcnt(1)
	v_mfma_f32_32x32x16_bf16 v[16:31], v[0:3], v[120:123], v[16:31]
	v_or_b32_e32 v0, 64, v180
	v_bitop3_b32 v0, v0, v12, v13 bitop3:0xde
	v_add_u32_e32 v193, 32, v0
	s_waitcnt lgkmcnt(0)
	v_mfma_f32_32x32x16_bf16 v[32:47], v[4:7], v[120:123], v[32:47]
	ds_read_b128 v[0:3], v193 offset:32768
	ds_read_b128 v[4:7], v193 offset:40960
	s_waitcnt lgkmcnt(1)
	v_mfma_f32_32x32x16_bf16 v[16:31], v[0:3], v[116:119], v[16:31]
	v_or_b32_e32 v0, 0x60, v180
	v_bitop3_b32 v0, v0, v12, v13 bitop3:0xde
	v_add_u32_e32 v190, 32, v0
	s_waitcnt lgkmcnt(0)
	v_mfma_f32_32x32x16_bf16 v[32:47], v[4:7], v[116:119], v[32:47]
	ds_read_b128 v[0:3], v190 offset:32768
	ds_read_b128 v[4:7], v190 offset:40960
	s_waitcnt lgkmcnt(1)
	v_mfma_f32_32x32x16_bf16 v[16:31], v[0:3], v[112:115], v[16:31]
	v_or_b32_e32 v0, 0x80, v180
	v_bitop3_b32 v0, v0, v12, v13 bitop3:0xde
	v_add_u32_e32 v191, 32, v0
	s_waitcnt lgkmcnt(0)
	v_mfma_f32_32x32x16_bf16 v[32:47], v[4:7], v[112:115], v[32:47]
	ds_read_b128 v[0:3], v191 offset:32768
	ds_read_b128 v[4:7], v191 offset:40960
	s_waitcnt lgkmcnt(1)
	v_mfma_f32_32x32x16_bf16 v[16:31], v[0:3], v[108:111], v[16:31]
	v_or_b32_e32 v0, 0xa0, v180
	v_bitop3_b32 v0, v0, v12, v13 bitop3:0xde
	v_add_u32_e32 v194, 32, v0
	ds_read_b128 v[0:3], v194 offset:32768
	s_waitcnt lgkmcnt(1)
	v_mfma_f32_32x32x16_bf16 v[32:47], v[4:7], v[108:111], v[32:47]
	v_and_b32_e32 v4, 0x3fffffc0, v247
	v_lshl_add_u32 v75, v4, 2, s21
	ds_read_b128 v[4:7], v194 offset:40960
	s_mov_b32 s21, 1
	v_lshl_add_u32 v182, v246, 2, v75
	v_add_u32_e32 v177, v75, v180
	s_waitcnt lgkmcnt(1)
	v_mfma_f32_32x32x16_bf16 v[16:31], v[0:3], v[104:107], v[16:31]
	v_lshl_add_u64 v[0:1], v[50:51], 0, s[26:27]
	s_mov_b64 s[26:27], 0xc000
	v_lshl_add_u64 v[2:3], s[6:7], 0, v[0:1]
	v_lshl_add_u64 v[8:9], v[50:51], 0, s[26:27]
	v_lshl_add_u64 v[0:1], s[18:19], 0, v[0:1]
	v_lshl_add_u64 v[10:11], s[6:7], 0, v[8:9]
	global_load_dwordx4 v[52:55], v[2:3], off
	global_load_dwordx4 v[56:59], v[10:11], off
	v_lshl_add_u64 v[2:3], s[18:19], 0, v[8:9]
	global_load_dwordx4 v[60:63], v[0:1], off
	global_load_dwordx4 v[64:67], v[2:3], off
	v_or_b32_e32 v0, 0xc0, v180
	v_bitop3_b32 v0, v0, v12, v13 bitop3:0xde
	v_add_u32_e32 v195, 32, v0
	ds_read_b128 v[0:3], v195 offset:32768
	v_lshlrev_b32_e32 v9, 1, v247
	v_and_or_b32 v8, v14, 24, v15
	s_waitcnt lgkmcnt(1)
	v_mfma_f32_32x32x16_bf16 v[32:47], v[4:7], v[104:107], v[32:47]
	v_and_b32_e32 v4, 32, v9
	v_and_b32_e32 v5, 0x100, v14
	v_or3_b32 v76, v8, v4, v5
	ds_read_b128 v[4:7], v195 offset:40960
	s_mov_b64 s[26:27], 0x14000
	v_add_u32_e32 v184, s25, v76
	s_waitcnt lgkmcnt(1)
	v_mfma_f32_32x32x16_bf16 v[16:31], v[0:3], v[100:103], v[16:31]
	v_or_b32_e32 v0, 0xe0, v180
	v_bitop3_b32 v0, v0, v12, v13 bitop3:0xde
	v_add_u32_e32 v196, 32, v0
	ds_read_b128 v[0:3], v196 offset:32768
	ds_read_b128 v[68:71], v196 offset:40960
	v_mov_b32_e32 v180, 0
	s_waitcnt lgkmcnt(2)
	v_mfma_f32_32x32x16_bf16 v[32:47], v[4:7], v[100:103], v[32:47]
	s_waitcnt lgkmcnt(1)
	v_mfma_f32_32x32x16_bf16 v[16:31], v[0:3], v[96:99], v[16:31]
	v_mov_b64_e32 v[0:1], s[36:37]
	v_mov_b64_e32 v[14:15], s[50:51]
	v_mov_b64_e32 v[2:3], s[38:39]
	v_mov_b64_e32 v[4:5], s[40:41]
	v_mov_b64_e32 v[6:7], s[42:43]
	v_mov_b64_e32 v[8:9], s[44:45]
	v_mov_b64_e32 v[10:11], s[46:47]
	s_waitcnt lgkmcnt(0)
	v_mfma_f32_32x32x16_bf16 v[32:47], v[68:71], v[96:99], v[32:47]
	s_nop 2
	v_max_f32_e32 v68, v17, v17
	v_max_f32_e32 v69, v16, v16
	v_max_f32_e32 v68, v69, v68
	v_max3_f32 v68, v68, v18, v19
	v_max3_f32 v68, v68, v20, v21
	v_max3_f32 v68, v68, v22, v23
	v_max3_f32 v68, v68, v24, v25
	v_max3_f32 v68, v68, v26, v27
	v_max3_f32 v68, v68, v28, v29
	v_max3_f32 v68, v68, v30, v31
	v_max3_f32 v68, v68, v32, v33
	v_max3_f32 v68, v68, v34, v35
	v_max3_f32 v68, v68, v36, v37
	v_max3_f32 v68, v68, v38, v39
	v_max3_f32 v68, v68, v40, v41
	v_max3_f32 v68, v68, v42, v43
	v_max3_f32 v68, v68, v44, v45
	v_max3_f32 v77, v68, v46, v47
	v_mov_b32_e32 v68, v77
	s_nop 1
	v_permlane32_swap_b32_e32 v77, v68
	v_max_f32_e32 v78, v68, v68
	v_lshl_add_u64 v[68:69], v[50:51], 0, s[26:27]
	s_mov_b64 s[26:27], 0x10000
	v_lshl_add_u64 v[70:71], s[18:19], 0, v[68:69]
	v_lshl_add_u64 v[50:51], v[50:51], 0, s[26:27]
	v_lshl_add_u64 v[68:69], s[6:7], 0, v[68:69]
	v_lshl_add_u64 v[72:73], s[18:19], 0, v[50:51]
	global_load_dwordx4 v[136:139], v[70:71], off
	global_load_dwordx4 v[128:131], v[72:73], off
	v_lshl_add_u64 v[50:51], s[6:7], 0, v[50:51]
	global_load_dwordx4 v[140:143], v[68:69], off
	global_load_dwordx4 v[132:135], v[50:51], off
	v_max_f32_e32 v50, v77, v77
	v_max_f32_e32 v50, v50, v78
	v_add_f32_e32 v51, 0x7149f2ca, v50
	v_max_f32_e32 v50, 0xf149f2ca, v50
	v_cmp_ge_f32_e32 vcc, s66, v51
	v_sub_f32_e32 v51, 0xf149f2ca, v50
	v_mul_f32_e32 v51, 0x3e0293ee, v51
	v_exp_f32_e32 v51, v51
	s_cmp_eq_u64 vcc, exec
	s_cselect_b64 vcc, -1, 0
	s_mov_b32 s6, 0x3e0293ee
	v_cndmask_b32_e64 v197, v51, 1.0, vcc
	v_mov_b32_e32 v51, 0xf149f2ca
	v_cndmask_b32_e32 v168, v50, v51, vcc
; #define SBAR() __builtin_amdgcn_sched_barrier(0)
; #define SWRITE(b, i) do { *(bf16x8*)((char*)V_lds + (b) * SHM_V + vst0) = sr_[i].vs0;          \
;     *(bf16x8*)((char*)V_lds + (b) * SHM_V + vst1) = sr_[i].vs1; int kc = sc * 2;               \
;     *(bf16x8*)((char*)K_lds + (b) * SHM_K + KSWZ(sr, kc)) = sr_[i].ks0;                       \
;     *(bf16x8*)((char*)K_lds + (b) * SHM_K + KSWZ(32 + sr, kc)) = sr_[i].ks1; } while (0)
; #define SWAIT() do { if constexpr (SDEPTH == 2) asm volatile("s_waitcnt vmcnt(4)" ::: "memory"); else asm volatile("s_waitcnt vmcnt(0)" ::: "memory"); } while (0)
; template <bool BAND>
; __device__ __forceinline__ void partialSM(f32x16& p0, f32x16& p1, float& m_reg, float& mn, float& alpha, int drel) {
;     ...
;   float mnC = -mn * C;
; #pragma unroll
;   for (int r = 0; r < 16; ++r) p0[r] = fmaf(p0[r], C, mnC);
; #pragma unroll
;   for (int r = 0; r < 16; ++r) p1[r] = fmaf(p1[r], C, mnC);
; #pragma unroll
;   for (int r = 0; r < 16; ++r) p0[r] = __builtin_amdgcn_exp2f(p0[r]);
; template <bool BAND>
; __device__ __forceinline__ void attn_body(const u16* Qb, const u16* __restrict__ Kh, const u16* __restrict__ Vh, u16* Ob, int NT, int kpos0, int qpos0, float sink_l2, char* lds, const float* __restrict__ qn) {
;     ...
;   SWAIT(); SWRITE(1, SO); __syncthreads();
;   for (int j = 1; j + 1 < NT; j += 2) {
;     SBAR(); qkt(pB0, pB1, (u16*)((char*)K_lds + SHM_K), qr, r32, hi);
;     finishSM(pA0, pA1, alA, l_reg, pa0, pa1, pa2, pa3); SBAR();
	v_mul_f32_e32 v50, 0xbe0293ee, v168
	v_fmamk_f32 v16, v16, 0x3e0293ee, v50
	v_exp_f32_e32 v161, v16
	v_fmamk_f32 v16, v17, 0x3e0293ee, v50
	v_exp_f32_e32 v175, v16
	v_fmamk_f32 v16, v18, 0x3e0293ee, v50
	v_exp_f32_e32 v162, v16
	v_fmamk_f32 v16, v19, 0x3e0293ee, v50
	v_exp_f32_e32 v201, v16
	v_fmamk_f32 v16, v20, 0x3e0293ee, v50
	v_exp_f32_e32 v174, v16
	v_fmamk_f32 v16, v21, 0x3e0293ee, v50
	v_exp_f32_e32 v204, v16
	v_fmamk_f32 v16, v22, 0x3e0293ee, v50
	v_exp_f32_e32 v163, v16
	v_fmamk_f32 v16, v23, 0x3e0293ee, v50
	v_exp_f32_e32 v173, v16
	v_fmamk_f32 v16, v24, 0x3e0293ee, v50
	v_exp_f32_e32 v164, v16
	v_fmamk_f32 v16, v25, 0x3e0293ee, v50
	v_exp_f32_e32 v171, v16
	v_fmamk_f32 v16, v26, 0x3e0293ee, v50
	v_exp_f32_e32 v165, v16
	v_fmamk_f32 v16, v27, 0x3e0293ee, v50
	v_exp_f32_e32 v172, v16
	v_fmamk_f32 v16, v28, 0x3e0293ee, v50
	v_exp_f32_e32 v166, v16
	v_fmamk_f32 v16, v29, 0x3e0293ee, v50
	v_exp_f32_e32 v169, v16
	v_fmamk_f32 v16, v30, 0x3e0293ee, v50
	v_exp_f32_e32 v167, v16
	v_lshl_add_u64 v[16:17], s[8:9], 0, v[48:49]
	v_and_b32_e32 v18, 15, v247
	v_pk_fma_f32 v[146:147], v[46:47], s[6:7], v[50:51] op_sel_hi:[1,0,0]
	v_pk_fma_f32 v[150:151], v[44:45], s[6:7], v[50:51] op_sel_hi:[1,0,0]
	v_pk_fma_f32 v[154:155], v[42:43], s[6:7], v[50:51] op_sel_hi:[1,0,0]
	v_pk_fma_f32 v[144:145], v[40:41], s[6:7], v[50:51] op_sel_hi:[1,0,0]
	v_pk_fma_f32 v[148:149], v[38:39], s[6:7], v[50:51] op_sel_hi:[1,0,0]
	v_pk_fma_f32 v[152:153], v[36:37], s[6:7], v[50:51] op_sel_hi:[1,0,0]
	v_pk_fma_f32 v[156:157], v[34:35], s[6:7], v[50:51] op_sel_hi:[1,0,0]
	v_pk_fma_f32 v[158:159], v[32:33], s[6:7], v[50:51] op_sel_hi:[1,0,0]
	v_fmac_f32_e32 v50, 0x3e0293ee, v31
	v_lshlrev_b64 v[16:17], 9, v[16:17]
	v_lshlrev_b32_e32 v18, 4, v18
	v_exp_f32_e32 v170, v50
	v_or3_b32 v16, v16, s24, v18
	s_waitcnt vmcnt(4)
	v_lshl_add_u64 v[16:17], s[10:11], 0, v[16:17]
	s_mov_b64 s[8:9], 0x20824000
	v_mov_b64_e32 v[12:13], s[48:49]
	s_waitcnt vmcnt(7)
	ds_write_b128 v185, v[52:55] offset:16384
	s_waitcnt vmcnt(6)
	ds_write_b128 v186, v[56:59] offset:16384
	s_waitcnt vmcnt(5)
	ds_write_b128 v187, v[60:63] offset:49152
	s_waitcnt vmcnt(4)
	ds_write_b128 v188, v[64:67] offset:49152
	s_addk_i32 s25, 0x4000
	v_lshl_add_u64 v[178:179], v[16:17], 0, s[8:9]
	v_mov_b64_e32 v[62:63], v[14:15]
	v_mov_b64_e32 v[46:47], v[14:15]
	v_mov_b64_e32 v[30:31], v[14:15]
	v_cmp_gt_u32_e64 s[6:7], 32, v74
	v_add_u32_e32 v183, s25, v76
	v_mov_b64_e32 v[60:61], v[12:13]
	v_mov_b64_e32 v[58:59], v[10:11]
	v_mov_b64_e32 v[56:57], v[8:9]
	v_mov_b64_e32 v[54:55], v[6:7]
	v_mov_b64_e32 v[52:53], v[4:5]
	v_mov_b64_e32 v[50:51], v[2:3]
	v_mov_b64_e32 v[48:49], v[0:1]
	v_mov_b64_e32 v[44:45], v[12:13]
	v_mov_b64_e32 v[42:43], v[10:11]
	v_mov_b64_e32 v[40:41], v[8:9]
	v_mov_b64_e32 v[38:39], v[6:7]
	v_mov_b64_e32 v[36:37], v[4:5]
	v_mov_b64_e32 v[34:35], v[2:3]
	v_mov_b64_e32 v[32:33], v[0:1]
	v_mov_b64_e32 v[28:29], v[12:13]
	v_mov_b64_e32 v[26:27], v[10:11]
	v_mov_b64_e32 v[24:25], v[8:9]
	v_mov_b64_e32 v[22:23], v[6:7]
	v_mov_b64_e32 v[20:21], v[4:5]
	v_mov_b64_e32 v[18:19], v[2:3]
	v_mov_b64_e32 v[16:17], v[0:1]
	s_waitcnt lgkmcnt(0)
	s_barrier
	v_readfirstlane_b32 s8, v224
	s_nop 3
	s_bfe_u32 s8, s8, 0x30006
	s_cmp_ge_u32 s8, 4
	s_cbranch_scc0 .Lmy_att_prio_skip
	s_setprio 1
.Lmy_att_prio_skip:
.LBB0_1644:
	ds_read_b128 v[64:67], v189 offset:49152
	ds_read_b128 v[68:71], v189 offset:57344
	ds_read_b128 v[206:209], v192 offset:49152
	ds_read_b128 v[210:213], v192 offset:57344
	v_add_f32_e32 v160, 0, v161
	v_add_f32_e32 v160, v175, v160
	s_waitcnt lgkmcnt(3)
	v_mfma_f32_32x32x16_bf16 v[80:95], v[64:67], v[124:127], 0
	v_add_f32_e32 v160, v162, v160
	v_add_f32_e32 v160, v201, v160
	v_add_f32_e32 v160, v174, v160
	v_add_f32_e32 v160, v204, v160
	v_add_f32_e32 v160, v163, v160
	v_add_f32_e32 v160, v173, v160
	v_add_f32_e32 v160, v164, v160
	s_waitcnt lgkmcnt(2)
	v_mfma_f32_32x32x16_bf16 v[64:79], v[68:71], v[124:127], 0
	v_add_f32_e32 v160, v171, v160
	v_add_f32_e32 v160, v165, v160
	v_add_f32_e32 v160, v172, v160
	v_exp_f32_e32 v158, v158
	v_add_f32_e32 v160, v166, v160
	v_exp_f32_e32 v159, v159
	v_add_f32_e32 v160, v169, v160
	s_waitcnt lgkmcnt(1)
	v_mfma_f32_32x32x16_bf16 v[80:95], v[206:209], v[120:123], v[80:95]
	v_exp_f32_e32 v156, v156
	v_add_f32_e32 v160, v167, v160
	v_exp_f32_e32 v157, v157
	v_add_f32_e32 v160, v170, v160
	v_exp_f32_e32 v152, v152
	v_add_f32_e32 v160, v158, v160
	v_exp_f32_e32 v153, v153
	s_waitcnt lgkmcnt(0)
	v_mfma_f32_32x32x16_bf16 v[64:79], v[210:213], v[120:123], v[64:79]
	ds_read_b128 v[206:209], v193 offset:49152
	ds_read_b128 v[210:213], v193 offset:57344
	v_add_f32_e32 v160, v159, v160
	v_exp_f32_e32 v148, v148
	v_add_f32_e32 v160, v156, v160
	v_exp_f32_e32 v149, v149
	v_add_f32_e32 v160, v157, v160
	v_exp_f32_e32 v144, v144
	s_waitcnt lgkmcnt(1)
	v_mfma_f32_32x32x16_bf16 v[80:95], v[206:209], v[116:119], v[80:95]
	v_add_f32_e32 v160, v152, v160
	v_exp_f32_e32 v145, v145
	v_add_f32_e32 v160, v153, v160
	v_exp_f32_e32 v154, v154
	v_add_f32_e32 v160, v148, v160
	v_exp_f32_e32 v155, v155
	v_add_f32_e32 v160, v149, v160
	s_waitcnt lgkmcnt(0)
	v_mfma_f32_32x32x16_bf16 v[64:79], v[210:213], v[116:119], v[64:79]
	ds_read_b128 v[206:209], v190 offset:49152
	ds_read_b128 v[210:213], v190 offset:57344
	v_exp_f32_e32 v150, v150
	v_add_f32_e32 v160, v144, v160
	v_exp_f32_e32 v151, v151
	v_add_f32_e32 v160, v145, v160
	v_exp_f32_e32 v146, v146
	v_add_f32_e32 v160, v154, v160
	s_waitcnt lgkmcnt(1)
	v_mfma_f32_32x32x16_bf16 v[80:95], v[206:209], v[112:115], v[80:95]
	v_exp_f32_e32 v147, v147
	v_add_f32_e32 v160, v155, v160
	v_add_f32_e32 v160, v150, v160
	v_add_f32_e32 v160, v151, v160
	v_add_f32_e32 v160, v146, v160
	v_add_f32_e32 v198, v147, v160
	v_mov_b32_e32 v199, v198
	s_waitcnt lgkmcnt(0)
; #define SBAR() __builtin_amdgcn_sched_barrier(0)
; #define SLOAD(i, k0) do { sr_[i].vs0 = *reinterpret_cast<const bf16x8*>(&Vh[(long)((k0) + sr) * LDK + sc]); sr_[i].vs1 = *reinterpret_cast<const bf16x8*>(&Vh[(long)((k0) + 32 + sr) * LDK + sc]); \
;     sr_[i].ks0 = *reinterpret_cast<const bf16x8*>(&Kh[(long)((k0) + sr) * LDK + sc]); sr_[i].ks1 = *reinterpret_cast<const bf16x8*>(&Kh[(long)((k0) + 32 + sr) * LDK + sc]); } while (0)
; template <bool BAND>
; __device__ __forceinline__ void attn_body(const u16* Qb, const u16* __restrict__ Kh, const u16* __restrict__ Vh, u16* Ob, int NT, int kpos0, int qpos0, float sink_l2, char* lds, const float* __restrict__ qn) {
;     ...
;     SBAR(); qkt(pB0, pB1, (u16*)((char*)K_lds + SHM_K), qr, r32, hi);
;     finishSM(pA0, pA1, alA, l_reg, pa0, pa1, pa2, pa3); SBAR();
;     SLOAD(SO, (j + SDEPTH) * KVBLK); SBAR();
;     pv_d0(o, vb0, pa0, pa1, pa2, pa3); partialSM<BAND>(pB0, pB1, m_reg, mnB, alB, dq + j * KVBLK);
	v_mfma_f32_32x32x16_bf16 v[64:79], v[210:213], v[112:115], v[64:79]
	ds_read_b128 v[206:209], v191 offset:49152
	ds_read_b128 v[210:213], v191 offset:57344
	v_permlane32_swap_b32_e32 v198, v199
	s_waitcnt lgkmcnt(1)
	v_mfma_f32_32x32x16_bf16 v[80:95], v[206:209], v[108:111], v[80:95]
	s_waitcnt lgkmcnt(0)
	v_mfma_f32_32x32x16_bf16 v[64:79], v[210:213], v[108:111], v[64:79]
	ds_read_b128 v[206:209], v194 offset:49152
	ds_read_b128 v[210:213], v194 offset:57344
	s_waitcnt lgkmcnt(1)
	v_mfma_f32_32x32x16_bf16 v[80:95], v[206:209], v[104:107], v[80:95]
	s_waitcnt lgkmcnt(0)
	v_mfma_f32_32x32x16_bf16 v[64:79], v[210:213], v[104:107], v[64:79]
	ds_read_b128 v[206:209], v195 offset:49152
	ds_read_b128 v[210:213], v195 offset:57344
	s_waitcnt lgkmcnt(1)
	v_mfma_f32_32x32x16_bf16 v[80:95], v[206:209], v[100:103], v[80:95]
	s_waitcnt lgkmcnt(0)
	v_mfma_f32_32x32x16_bf16 v[64:79], v[210:213], v[100:103], v[64:79]
	ds_read_b128 v[206:209], v196 offset:49152
	ds_read_b128 v[210:213], v196 offset:57344
	v_cvt_pk_bf16_f32 v160, v161, v175
	v_cvt_pk_bf16_f32 v161, v162, v201
	v_cvt_pk_bf16_f32 v162, v174, v204
	v_cvt_pk_bf16_f32 v163, v163, v173
	v_cvt_pk_bf16_f32 v164, v164, v171
	v_cvt_pk_bf16_f32 v165, v165, v172
	s_waitcnt lgkmcnt(1)
	v_mfma_f32_32x32x16_bf16 v[80:95], v[206:209], v[96:99], v[80:95]
	v_cvt_pk_bf16_f32 v166, v166, v169
	v_cvt_pk_bf16_f32 v167, v167, v170
	v_cvt_pk_bf16_f32 v170, v158, v159
	v_cvt_pk_bf16_f32 v171, v156, v157
	v_cvt_pk_bf16_f32 v172, v152, v153
	v_cvt_pk_bf16_f32 v173, v148, v149
	v_cvt_pk_bf16_f32 v200, v144, v145
	s_waitcnt lgkmcnt(0)
	v_mfma_f32_32x32x16_bf16 v[64:79], v[210:213], v[96:99], v[64:79]
	v_cvt_pk_bf16_f32 v201, v154, v155
	v_cvt_pk_bf16_f32 v202, v150, v151
	v_permlane32_swap_b32_e32 v160, v162
	v_cvt_pk_bf16_f32 v203, v146, v147
	v_permlane32_swap_b32_e32 v200, v202
	v_permlane32_swap_b32_e32 v161, v163
	v_permlane32_swap_b32_e32 v164, v166
	v_permlane32_swap_b32_e32 v165, v167
	v_permlane32_swap_b32_e32 v170, v172
	v_permlane32_swap_b32_e32 v171, v173
	v_permlane32_swap_b32_e32 v201, v203
	s_mov_b32 s8, 0xffff4000
	v_add_co_u32_e32 v144, vcc, s8, v178
	s_movk_i32 s8, 0x8000
	s_nop 0
	v_addc_co_u32_e32 v145, vcc, -1, v179, vcc
	v_add_co_u32_e32 v148, vcc, s8, v178
	s_mov_b32 s8, 0xfdff4000
	s_nop 0
	v_addc_co_u32_e32 v149, vcc, -1, v179, vcc
	v_add_co_u32_e32 v152, vcc, s8, v178
	s_mov_b32 s8, 0xfdff8000
	s_nop 0
	v_addc_co_u32_e32 v153, vcc, -1, v179, vcc
	v_add_co_u32_e32 v156, vcc, s8, v178
	global_load_dwordx4 v[144:147], v[144:145], off
	s_nop 0
	global_load_dwordx4 v[148:151], v[148:149], off
	v_addc_co_u32_e32 v157, vcc, -1, v179, vcc
	global_load_dwordx4 v[152:155], v[152:153], off
	s_nop 0
	global_load_dwordx4 v[156:159], v[156:157], off
	ds_read_b64_tr_b16 v[204:205], v184 offset:0
	ds_read_b64_tr_b16 v[206:207], v184 offset:0x800
	ds_read_b64_tr_b16 v[208:209], v184 offset:0x1000
	ds_read_b64_tr_b16 v[210:211], v184 offset:0x1800
	ds_read_b64_tr_b16 v[212:213], v184 offset:0x2000
	ds_read_b64_tr_b16 v[214:215], v184 offset:0x2800
	ds_read_b64_tr_b16 v[216:217], v184 offset:0x3000
	ds_read_b64_tr_b16 v[218:219], v184 offset:0x3800
	s_waitcnt lgkmcnt(0)
	s_nop 0
	v_mfma_f32_32x32x16_bf16 v[0:15], v[160:163], v[204:207], v[0:15]
	v_max_f32_e32 v234, v81, v81
	v_max_f32_e32 v235, v80, v80
	v_max_f32_e32 v234, v235, v234
	v_max3_f32 v234, v234, v82, v83
	v_max3_f32 v234, v234, v84, v85
	v_max3_f32 v234, v234, v86, v87
	s_waitcnt vmcnt(4)
	ds_write_b128 v187, v[128:131] offset:32768
	ds_write_b128 v188, v[136:139] offset:32768
	ds_read_b64_tr_b16 v[204:205], v184 offset:0x200
	ds_read_b64_tr_b16 v[206:207], v184 offset:0xa00
	v_mfma_f32_32x32x16_bf16 v[0:15], v[164:167], v[208:211], v[0:15]
	v_max3_f32 v234, v234, v88, v89
	v_max3_f32 v234, v234, v90, v91
	v_max3_f32 v234, v234, v92, v93
	v_max3_f32 v234, v234, v94, v95
	v_max3_f32 v234, v234, v64, v65
	v_max3_f32 v234, v234, v66, v67
	ds_read_b64_tr_b16 v[208:209], v184 offset:0x1200
	ds_read_b64_tr_b16 v[210:211], v184 offset:0x1a00
	v_mfma_f32_32x32x16_bf16 v[0:15], v[170:173], v[212:215], v[0:15]
	v_max3_f32 v234, v234, v68, v69
	v_max3_f32 v234, v234, v70, v71
	v_max3_f32 v234, v234, v72, v73
	v_max3_f32 v234, v234, v74, v75
	v_max3_f32 v234, v234, v76, v77
	v_max3_f32 v234, v234, v78, v79
	ds_read_b64_tr_b16 v[212:213], v184 offset:0x2200
	ds_read_b64_tr_b16 v[214:215], v184 offset:0x2a00
	v_mfma_f32_32x32x16_bf16 v[0:15], v[200:203], v[216:219], v[0:15]
	v_mov_b32_e32 v235, v234
	s_nop 1
	v_permlane32_swap_b32_e32 v234, v235
	v_max_f32_e32 v235, v235, v235
	v_max_f32_e32 v234, v234, v234
	v_max_f32_e32 v234, v234, v235
	ds_read_b64_tr_b16 v[216:217], v184 offset:0x3200
	ds_read_b64_tr_b16 v[218:219], v184 offset:0x3a00
	s_waitcnt lgkmcnt(0)
; #define SWRITE(b, i) do { *(bf16x8*)((char*)V_lds + (b) * SHM_V + vst0) = sr_[i].vs0;          \
;     *(bf16x8*)((char*)V_lds + (b) * SHM_V + vst1) = sr_[i].vs1; int kc = sc * 2;               \
;     *(bf16x8*)((char*)K_lds + (b) * SHM_K + KSWZ(sr, kc)) = sr_[i].ks0;                       \
;     *(bf16x8*)((char*)K_lds + (b) * SHM_K + KSWZ(32 + sr, kc)) = sr_[i].ks1; } while (0)
; #define SWAIT() do { if constexpr (SDEPTH == 2) asm volatile("s_waitcnt vmcnt(4)" ::: "memory"); else asm volatile("s_waitcnt vmcnt(0)" ::: "memory"); } while (0)
; #define RESC(a) do { if (__any((a) < 1.f)) { if (hi == 0) al_l[r32] = (a); asm volatile("s_waitcnt lgkmcnt(0)" ::: "memory"); \
;     for (int d = 0; d < 4; ++d) for (int r = 0; r < 16; ++r) o[d][r] *= al_l[crow(r, hi)]; } } while (0)
; template <bool BAND>
; __device__ __forceinline__ void attn_body(const u16* Qb, const u16* __restrict__ Kh, const u16* __restrict__ Vh, u16* Ob, int NT, int kpos0, int qpos0, float sink_l2, char* lds, const float* __restrict__ qn) {
;     ...
;     pv_d0(o, vb0, pa0, pa1, pa2, pa3); partialSM<BAND>(pB0, pB1, m_reg, mnB, alB, dq + j * KVBLK);
;     __syncthreads(); SWAIT(); SWRITE(0, SE);
;     RESC(alB); __syncthreads();
	v_mfma_f32_32x32x16_bf16 v[48:63], v[160:163], v[204:207], v[48:63]
	v_sub_f32_e32 v235, v234, v168
	v_cmp_ge_f32_e32 vcc, s66, v235
	v_max_f32_e32 v235, v168, v168
	v_max_f32_e32 v234, v235, v234
	v_sub_f32_e32 v235, v168, v234
	v_mul_f32_e32 v235, 0x3e0293ee, v235
	ds_read_b64_tr_b16 v[204:205], v184 offset:0x400
	ds_read_b64_tr_b16 v[206:207], v184 offset:0xc00
	v_mfma_f32_32x32x16_bf16 v[48:63], v[164:167], v[208:211], v[48:63]
	v_exp_f32_e32 v235, v235
	s_cmp_eq_u64 vcc, exec
	s_cselect_b64 s[8:9], -1, 0
	s_nop 0
	v_cndmask_b32_e64 v236, v234, v168, s[8:9]
	v_mul_f32_e32 v237, 0xbe0293ee, v236
	ds_read_b64_tr_b16 v[208:209], v184 offset:0x1400
	ds_read_b64_tr_b16 v[210:211], v184 offset:0x1c00
	v_mfma_f32_32x32x16_bf16 v[48:63], v[170:173], v[212:215], v[48:63]
	ds_read_b64_tr_b16 v[212:213], v184 offset:0x2400
	ds_read_b64_tr_b16 v[214:215], v184 offset:0x2c00
	v_mfma_f32_32x32x16_bf16 v[48:63], v[200:203], v[216:219], v[48:63]
	v_fmamk_f32 v80, v80, 0x3e0293ee, v237
	v_fmamk_f32 v81, v81, 0x3e0293ee, v237
	v_fmamk_f32 v82, v82, 0x3e0293ee, v237
	v_fmamk_f32 v83, v83, 0x3e0293ee, v237
	ds_read_b64_tr_b16 v[216:217], v184 offset:0x3400
	ds_read_b64_tr_b16 v[218:219], v184 offset:0x3c00
	s_waitcnt lgkmcnt(0)
	v_mfma_f32_32x32x16_bf16 v[32:47], v[160:163], v[204:207], v[32:47]
	v_fmamk_f32 v84, v84, 0x3e0293ee, v237
	v_fmamk_f32 v85, v85, 0x3e0293ee, v237
	v_fmamk_f32 v86, v86, 0x3e0293ee, v237
	v_fmamk_f32 v87, v87, 0x3e0293ee, v237
	ds_read_b64_tr_b16 v[204:205], v184 offset:0x600
	ds_read_b64_tr_b16 v[206:207], v184 offset:0xe00
	v_mfma_f32_32x32x16_bf16 v[32:47], v[164:167], v[208:211], v[32:47]
	v_fmamk_f32 v88, v88, 0x3e0293ee, v237
	v_fmamk_f32 v89, v89, 0x3e0293ee, v237
	v_fmamk_f32 v90, v90, 0x3e0293ee, v237
	v_fmamk_f32 v91, v91, 0x3e0293ee, v237
	ds_read_b64_tr_b16 v[208:209], v184 offset:0x1600
	ds_read_b64_tr_b16 v[210:211], v184 offset:0x1e00
	v_mfma_f32_32x32x16_bf16 v[32:47], v[170:173], v[212:215], v[32:47]
	v_fmamk_f32 v92, v92, 0x3e0293ee, v237
	v_fmamk_f32 v93, v93, 0x3e0293ee, v237
	v_fmamk_f32 v94, v94, 0x3e0293ee, v237
	v_fmamk_f32 v95, v95, 0x3e0293ee, v237
	ds_read_b64_tr_b16 v[212:213], v184 offset:0x2600
	ds_read_b64_tr_b16 v[214:215], v184 offset:0x2e00
	v_mfma_f32_32x32x16_bf16 v[32:47], v[200:203], v[216:219], v[32:47]
	v_exp_f32_e32 v175, v81
	v_exp_f32_e32 v174, v83
	v_exp_f32_e32 v169, v93
	v_exp_f32_e32 v168, v95
	ds_read_b64_tr_b16 v[216:217], v184 offset:0x3600
	ds_read_b64_tr_b16 v[218:219], v184 offset:0x3e00
	s_waitcnt lgkmcnt(0)
	v_mfma_f32_32x32x16_bf16 v[16:31], v[160:163], v[204:207], v[16:31]
	v_exp_f32_e32 v160, v80
	v_exp_f32_e32 v161, v82
	v_exp_f32_e32 v162, v84
	v_exp_f32_e32 v163, v86
	v_fmamk_f32 v204, v69, 0x3e0293ee, v237
	v_fmamk_f32 v205, v70, 0x3e0293ee, v237
	v_fmamk_f32 v206, v71, 0x3e0293ee, v237
	v_fmamk_f32 v207, v72, 0x3e0293ee, v237
	v_mfma_f32_32x32x16_bf16 v[16:31], v[164:167], v[208:211], v[16:31]
	v_exp_f32_e32 v164, v88
	v_exp_f32_e32 v165, v90
	v_exp_f32_e32 v166, v92
	v_exp_f32_e32 v167, v94
	v_fmamk_f32 v208, v73, 0x3e0293ee, v237
	v_fmamk_f32 v209, v74, 0x3e0293ee, v237
	v_fmamk_f32 v210, v75, 0x3e0293ee, v237
	v_fmamk_f32 v211, v64, 0x3e0293ee, v237
	v_mfma_f32_32x32x16_bf16 v[16:31], v[170:173], v[212:215], v[16:31]
	v_exp_f32_e32 v173, v85
	v_exp_f32_e32 v172, v87
	v_exp_f32_e32 v171, v89
	v_exp_f32_e32 v170, v91
	v_fmamk_f32 v212, v65, 0x3e0293ee, v237
	v_fmamk_f32 v213, v66, 0x3e0293ee, v237
	v_fmamk_f32 v214, v67, 0x3e0293ee, v237
	v_fmamk_f32 v215, v68, 0x3e0293ee, v237
	v_mfma_f32_32x32x16_bf16 v[16:31], v[200:203], v[216:219], v[16:31]
	v_fmamk_f32 v203, v76, 0x3e0293ee, v237
	v_fmamk_f32 v216, v77, 0x3e0293ee, v237
	v_fmamk_f32 v217, v78, 0x3e0293ee, v237
	v_fmamk_f32 v202, v79, 0x3e0293ee, v237
	v_mov_b32_e32 v201, v236
	s_barrier
	s_waitcnt vmcnt(4)
	v_cndmask_b32_e64 v200, v235, 1.0, s[8:9]
	v_cmp_gt_f32_e32 vcc, 1.0, v200
	s_waitcnt vmcnt(4)
	ds_write_b128 v185, v[132:135]
	ds_write_b128 v186, v[140:143]
	s_cbranch_vccz .LBB0_1648
	s_and_saveexec_b64 s[18:19], s[6:7]
	ds_write_b32 v182, v200 offset:128
	s_or_b64 exec, exec, s[18:19]
	s_waitcnt lgkmcnt(0)
	ds_read_b128 v[128:131], v177 offset:224
	ds_read_b128 v[132:135], v177 offset:192
	ds_read_b128 v[136:139], v177 offset:160
	ds_read_b128 v[140:143], v177 offset:128
	s_waitcnt lgkmcnt(3)
	v_pk_mul_f32 v[14:15], v[14:15], v[130:131]
	s_waitcnt lgkmcnt(2)
	v_pk_mul_f32 v[10:11], v[10:11], v[134:135]
	s_waitcnt lgkmcnt(1)
	v_pk_mul_f32 v[6:7], v[6:7], v[138:139]
	s_waitcnt lgkmcnt(0)
	v_pk_mul_f32 v[2:3], v[2:3], v[142:143]
	v_pk_mul_f32 v[12:13], v[12:13], v[128:129]
	v_pk_mul_f32 v[8:9], v[8:9], v[132:133]
	v_pk_mul_f32 v[4:5], v[4:5], v[136:137]
	v_pk_mul_f32 v[0:1], v[0:1], v[140:141]
	v_pk_mul_f32 v[62:63], v[62:63], v[130:131]
	v_pk_mul_f32 v[58:59], v[58:59], v[134:135]
	v_pk_mul_f32 v[54:55], v[54:55], v[138:139]
	v_pk_mul_f32 v[50:51], v[50:51], v[142:143]
	v_pk_mul_f32 v[60:61], v[60:61], v[128:129]
	v_pk_mul_f32 v[56:57], v[56:57], v[132:133]
	v_pk_mul_f32 v[52:53], v[52:53], v[136:137]
	v_pk_mul_f32 v[48:49], v[48:49], v[140:141]
	v_pk_mul_f32 v[46:47], v[46:47], v[130:131]
	v_pk_mul_f32 v[42:43], v[42:43], v[134:135]
	v_pk_mul_f32 v[38:39], v[38:39], v[138:139]
	v_pk_mul_f32 v[34:35], v[34:35], v[142:143]
	v_pk_mul_f32 v[44:45], v[44:45], v[128:129]
	v_pk_mul_f32 v[40:41], v[40:41], v[132:133]
	v_pk_mul_f32 v[36:37], v[36:37], v[136:137]
	v_pk_mul_f32 v[32:33], v[32:33], v[140:141]
	v_pk_mul_f32 v[30:31], v[30:31], v[130:131]
	v_pk_mul_f32 v[26:27], v[26:27], v[134:135]
	v_pk_mul_f32 v[22:23], v[22:23], v[138:139]
	v_pk_mul_f32 v[18:19], v[18:19], v[142:143]
	v_pk_mul_f32 v[28:29], v[28:29], v[128:129]
	v_pk_mul_f32 v[24:25], v[24:25], v[132:133]
	v_pk_mul_f32 v[20:21], v[20:21], v[136:137]
	v_pk_mul_f32 v[16:17], v[16:17], v[140:141]

; #define SBAR() __builtin_amdgcn_sched_barrier(0)
; template <bool BAND>
; __device__ __forceinline__ void attn_body(const u16* Qb, const u16* __restrict__ Kh, const u16* __restrict__ Vh, u16* Ob, int NT, int kpos0, int qpos0, float sink_l2, char* lds, const float* __restrict__ qn) {
;     ...
;   SBAR(); qkt(pB0, pB1, (u16*)((char*)K_lds + SHM_K), qr, r32, hi);
;   finishSM(pA0, pA1, alA, l_reg, pa0, pa1, pa2, pa3); SBAR();
;   pv_d0(o, vb0, pa0, pa1, pa2, pa3); partialSM<BAND>(pB0, pB1, m_reg, mnB, alB, dq + (NT - 1) * KVBLK);
.LBB0_1656:
	s_setprio 0
	ds_read_b128 v[64:67], v189 offset:49152
	ds_read_b128 v[68:71], v189 offset:57344
	s_waitcnt lgkmcnt(1)
	v_mfma_f32_32x32x16_bf16 v[80:95], v[64:67], v[124:127], 0
	s_waitcnt lgkmcnt(0)
	v_mfma_f32_32x32x16_bf16 v[64:79], v[68:71], v[124:127], 0
	ds_read_b128 v[124:127], v192 offset:49152
	ds_read_b128 v[128:131], v192 offset:57344
	s_waitcnt lgkmcnt(1)
	v_mfma_f32_32x32x16_bf16 v[80:95], v[124:127], v[120:123], v[80:95]
	s_waitcnt lgkmcnt(0)
	v_mfma_f32_32x32x16_bf16 v[64:79], v[128:131], v[120:123], v[64:79]
	ds_read_b128 v[120:123], v193 offset:49152
	ds_read_b128 v[124:127], v193 offset:57344
	s_waitcnt lgkmcnt(1)
	v_mfma_f32_32x32x16_bf16 v[80:95], v[120:123], v[116:119], v[80:95]
	s_waitcnt lgkmcnt(0)
	v_mfma_f32_32x32x16_bf16 v[64:79], v[124:127], v[116:119], v[64:79]
	ds_read_b128 v[116:119], v190 offset:49152
	ds_read_b128 v[120:123], v190 offset:57344
	s_waitcnt lgkmcnt(1)
	v_mfma_f32_32x32x16_bf16 v[80:95], v[116:119], v[112:115], v[80:95]
	s_waitcnt lgkmcnt(0)
	v_mfma_f32_32x32x16_bf16 v[64:79], v[120:123], v[112:115], v[64:79]
	ds_read_b128 v[112:115], v191 offset:49152
	ds_read_b128 v[116:119], v191 offset:57344
	v_exp_f32_e32 v120, v146
	v_exp_f32_e32 v121, v147
	s_waitcnt lgkmcnt(1)
	v_mfma_f32_32x32x16_bf16 v[80:95], v[112:115], v[108:111], v[80:95]
	s_waitcnt lgkmcnt(0)
	v_mfma_f32_32x32x16_bf16 v[64:79], v[116:119], v[108:111], v[64:79]
	ds_read_b128 v[108:111], v194 offset:49152
	ds_read_b128 v[112:115], v194 offset:57344
	v_exp_f32_e32 v116, v154
	v_exp_f32_e32 v117, v155
	v_exp_f32_e32 v118, v150
	v_exp_f32_e32 v119, v151
	s_waitcnt lgkmcnt(1)
	v_mfma_f32_32x32x16_bf16 v[80:95], v[108:111], v[104:107], v[80:95]
	s_waitcnt lgkmcnt(0)
	v_mfma_f32_32x32x16_bf16 v[64:79], v[112:115], v[104:107], v[64:79]
	ds_read_b128 v[104:107], v195 offset:49152
	ds_read_b128 v[108:111], v195 offset:57344
	v_exp_f32_e32 v112, v148
	v_exp_f32_e32 v113, v149
	v_exp_f32_e32 v114, v144
	v_exp_f32_e32 v115, v145
	s_waitcnt lgkmcnt(1)
	v_mfma_f32_32x32x16_bf16 v[80:95], v[104:107], v[100:103], v[80:95]
	s_waitcnt lgkmcnt(0)
	v_mfma_f32_32x32x16_bf16 v[64:79], v[108:111], v[100:103], v[64:79]
	ds_read_b128 v[100:103], v196 offset:49152
	ds_read_b128 v[104:107], v196 offset:57344
	v_exp_f32_e32 v108, v156
	v_exp_f32_e32 v109, v157
	v_exp_f32_e32 v110, v152
	v_exp_f32_e32 v111, v153
	s_waitcnt lgkmcnt(1)
	v_mfma_f32_32x32x16_bf16 v[80:95], v[100:103], v[96:99], v[80:95]
	s_waitcnt lgkmcnt(0)
	v_mfma_f32_32x32x16_bf16 v[64:79], v[104:107], v[96:99], v[64:79]
	v_add_f32_e32 v96, 0, v161
	v_add_f32_e32 v96, v175, v96
	v_add_f32_e32 v96, v162, v96
	v_add_f32_e32 v96, v201, v96
	v_add_f32_e32 v96, v174, v96
	v_add_f32_e32 v96, v204, v96
	v_add_f32_e32 v96, v163, v96
	v_add_f32_e32 v96, v173, v96
	v_add_f32_e32 v96, v164, v96
	v_add_f32_e32 v96, v171, v96
	v_add_f32_e32 v96, v165, v96
	v_add_f32_e32 v96, v172, v96
	v_exp_f32_e32 v106, v158
	v_add_f32_e32 v96, v166, v96
	v_exp_f32_e32 v107, v159
	v_add_f32_e32 v96, v169, v96
	v_add_f32_e32 v96, v167, v96
	v_add_f32_e32 v96, v170, v96
	v_add_f32_e32 v96, v106, v96
	v_add_f32_e32 v96, v107, v96
	v_add_f32_e32 v96, v108, v96
	v_add_f32_e32 v96, v109, v96
	v_add_f32_e32 v96, v110, v96
	v_add_f32_e32 v96, v111, v96
	v_add_f32_e32 v96, v112, v96
	v_add_f32_e32 v96, v113, v96
	v_add_f32_e32 v96, v114, v96
	v_add_f32_e32 v96, v115, v96
	v_add_f32_e32 v96, v116, v96
	v_add_f32_e32 v96, v117, v96
	v_add_f32_e32 v96, v118, v96
	v_add_f32_e32 v96, v119, v96
	v_add_f32_e32 v96, v120, v96
	v_add_f32_e32 v100, v121, v96
	v_mov_b32_e32 v101, v100
	v_cvt_pk_bf16_f32 v96, v161, v175
	v_cvt_pk_bf16_f32 v97, v162, v201
	v_cvt_pk_bf16_f32 v98, v174, v204
	v_cvt_pk_bf16_f32 v99, v163, v173
	s_nop 1
	v_permlane32_swap_b32_e32 v100, v101
	v_permlane32_swap_b32_e32 v96, v98
	v_permlane32_swap_b32_e32 v97, v99
	v_cvt_pk_bf16_f32 v102, v164, v171
	v_cvt_pk_bf16_f32 v103, v165, v172
	v_cvt_pk_bf16_f32 v104, v166, v169
	v_cvt_pk_bf16_f32 v105, v167, v170
	v_cvt_pk_bf16_f32 v106, v106, v107
	v_cvt_pk_bf16_f32 v107, v108, v109
	v_cvt_pk_bf16_f32 v108, v110, v111
	v_cvt_pk_bf16_f32 v109, v112, v113
	v_cvt_pk_bf16_f32 v110, v114, v115
	v_cvt_pk_bf16_f32 v111, v116, v117
	v_cvt_pk_bf16_f32 v112, v118, v119
	v_cvt_pk_bf16_f32 v113, v120, v121
	s_nop 0
	v_permlane32_swap_b32_e32 v102, v104
	v_permlane32_swap_b32_e32 v103, v105
	v_permlane32_swap_b32_e32 v106, v108
	v_permlane32_swap_b32_e32 v107, v109
	v_permlane32_swap_b32_e32 v110, v112
	v_permlane32_swap_b32_e32 v111, v113
	ds_read_b64_tr_b16 v[114:115], v184 offset:0
	ds_read_b64_tr_b16 v[116:117], v184 offset:0x800
	ds_read_b64_tr_b16 v[118:119], v184 offset:0x1000
	ds_read_b64_tr_b16 v[120:121], v184 offset:0x1800
	ds_read_b64_tr_b16 v[122:123], v184 offset:0x2000
	ds_read_b64_tr_b16 v[124:125], v184 offset:0x2800
	ds_read_b64_tr_b16 v[126:127], v184 offset:0x3000
	ds_read_b64_tr_b16 v[128:129], v184 offset:0x3800
	s_waitcnt lgkmcnt(0)
; #define RESC(a) do { if (__any((a) < 1.f)) { if (hi == 0) al_l[r32] = (a); asm volatile("s_waitcnt lgkmcnt(0)" ::: "memory"); \
;     for (int d = 0; d < 4; ++d) for (int r = 0; r < 16; ++r) o[d][r] *= al_l[crow(r, hi)]; } } while (0)
; template <bool BAND>
; __device__ __forceinline__ void attn_body(const u16* Qb, const u16* __restrict__ Kh, const u16* __restrict__ Vh, u16* Ob, int NT, int kpos0, int qpos0, float sink_l2, char* lds, const float* __restrict__ qn) {
;     ...
;   pv_d0(o, vb0, pa0, pa1, pa2, pa3); partialSM<BAND>(pB0, pB1, m_reg, mnB, alB, dq + (NT - 1) * KVBLK);
;   __syncthreads(); RESC(alB);
	s_nop 0
	v_mfma_f32_32x32x16_bf16 v[0:15], v[96:99], v[114:117], v[0:15]
	ds_read_b64_tr_b16 v[114:115], v184 offset:0x200
	ds_read_b64_tr_b16 v[116:117], v184 offset:0xa00
	v_mfma_f32_32x32x16_bf16 v[0:15], v[102:105], v[118:121], v[0:15]
	ds_read_b64_tr_b16 v[118:119], v184 offset:0x1200
	ds_read_b64_tr_b16 v[120:121], v184 offset:0x1a00
	v_mfma_f32_32x32x16_bf16 v[0:15], v[106:109], v[122:125], v[0:15]
	ds_read_b64_tr_b16 v[122:123], v184 offset:0x2200
	ds_read_b64_tr_b16 v[124:125], v184 offset:0x2a00
	v_mfma_f32_32x32x16_bf16 v[0:15], v[110:113], v[126:129], v[0:15]
	ds_read_b64_tr_b16 v[126:127], v184 offset:0x3200
	ds_read_b64_tr_b16 v[128:129], v184 offset:0x3a00
	s_waitcnt lgkmcnt(0)
	v_mfma_f32_32x32x16_bf16 v[48:63], v[96:99], v[114:117], v[48:63]
	ds_read_b64_tr_b16 v[114:115], v184 offset:0x400
	ds_read_b64_tr_b16 v[116:117], v184 offset:0xc00
	v_mfma_f32_32x32x16_bf16 v[48:63], v[102:105], v[118:121], v[48:63]
	ds_read_b64_tr_b16 v[118:119], v184 offset:0x1400
	ds_read_b64_tr_b16 v[120:121], v184 offset:0x1c00
	v_mfma_f32_32x32x16_bf16 v[48:63], v[106:109], v[122:125], v[48:63]
	ds_read_b64_tr_b16 v[122:123], v184 offset:0x2400
	ds_read_b64_tr_b16 v[124:125], v184 offset:0x2c00
	v_mfma_f32_32x32x16_bf16 v[48:63], v[110:113], v[126:129], v[48:63]
	ds_read_b64_tr_b16 v[126:127], v184 offset:0x3400
	ds_read_b64_tr_b16 v[128:129], v184 offset:0x3c00
	s_waitcnt lgkmcnt(0)
	v_mfma_f32_32x32x16_bf16 v[32:47], v[96:99], v[114:117], v[32:47]
	ds_read_b64_tr_b16 v[114:115], v184 offset:0x600
	ds_read_b64_tr_b16 v[116:117], v184 offset:0xe00
	v_mfma_f32_32x32x16_bf16 v[32:47], v[102:105], v[118:121], v[32:47]
	ds_read_b64_tr_b16 v[118:119], v184 offset:0x1600
	ds_read_b64_tr_b16 v[120:121], v184 offset:0x1e00
	v_mfma_f32_32x32x16_bf16 v[32:47], v[106:109], v[122:125], v[32:47]
	ds_read_b64_tr_b16 v[122:123], v184 offset:0x2600
	ds_read_b64_tr_b16 v[124:125], v184 offset:0x2e00
	v_mfma_f32_32x32x16_bf16 v[32:47], v[110:113], v[126:129], v[32:47]
	ds_read_b64_tr_b16 v[126:127], v184 offset:0x3600
	ds_read_b64_tr_b16 v[128:129], v184 offset:0x3e00
	s_waitcnt lgkmcnt(0)
	v_mfma_f32_32x32x16_bf16 v[16:31], v[96:99], v[114:117], v[16:31]
	v_max_f32_e32 v96, v81, v81
	v_max_f32_e32 v97, v80, v80
	v_max_f32_e32 v96, v97, v96
	v_max3_f32 v96, v96, v82, v83
	v_max3_f32 v96, v96, v84, v85
	v_max3_f32 v96, v96, v86, v87
	v_max3_f32 v96, v96, v88, v89
	v_max3_f32 v96, v96, v90, v91
	v_max3_f32 v96, v96, v92, v93
	v_mfma_f32_32x32x16_bf16 v[16:31], v[102:105], v[118:121], v[16:31]
	v_max3_f32 v96, v96, v94, v95
	v_max3_f32 v96, v96, v64, v65
	v_max3_f32 v96, v96, v66, v67
	v_max3_f32 v96, v96, v68, v69
	v_max3_f32 v96, v96, v70, v71
	v_max3_f32 v96, v96, v72, v73
	v_max3_f32 v96, v96, v74, v75
	v_max3_f32 v96, v96, v76, v77
	v_mfma_f32_32x32x16_bf16 v[16:31], v[106:109], v[122:125], v[16:31]
	v_max3_f32 v96, v96, v78, v79
	v_mov_b32_e32 v97, v96
	s_nop 1
	v_permlane32_swap_b32_e32 v96, v97
	v_max_f32_e32 v97, v97, v97
	v_max_f32_e32 v96, v96, v96
	v_max_f32_e32 v96, v96, v97
	v_sub_f32_e32 v97, v96, v168
	v_cmp_ge_f32_e32 vcc, s66, v97
	v_max_f32_e32 v97, v168, v168
	v_max_f32_e32 v97, v97, v96
	v_mfma_f32_32x32x16_bf16 v[16:31], v[110:113], v[126:129], v[16:31]
	v_sub_f32_e32 v96, v168, v97
	v_mul_f32_e32 v96, 0x3e0293ee, v96
	v_exp_f32_e32 v96, v96
	s_cmp_eq_u64 vcc, exec
	s_cselect_b64 s[8:9], -1, 0
	v_cndmask_b32_e64 v96, v96, 1.0, s[8:9]
	v_cmp_gt_f32_e32 vcc, 1.0, v96
	s_barrier
	s_cbranch_vccz .LBB0_1660
	s_and_saveexec_b64 s[18:19], s[6:7]
	ds_write_b32 v182, v96 offset:128
	s_or_b64 exec, exec, s[18:19]
	s_waitcnt lgkmcnt(0)
	ds_read_b128 v[102:105], v177 offset:224
	ds_read_b128 v[106:109], v177 offset:192
	ds_read_b128 v[110:113], v177 offset:160
	ds_read_b128 v[114:117], v177 offset:128
	s_waitcnt lgkmcnt(3)
	v_pk_mul_f32 v[14:15], v[14:15], v[104:105]
	s_waitcnt lgkmcnt(2)
	v_pk_mul_f32 v[10:11], v[10:11], v[108:109]
	s_waitcnt lgkmcnt(1)
	v_pk_mul_f32 v[6:7], v[6:7], v[112:113]
	s_waitcnt lgkmcnt(0)
	v_pk_mul_f32 v[2:3], v[2:3], v[116:117]
	v_pk_mul_f32 v[12:13], v[12:13], v[102:103]
	v_pk_mul_f32 v[8:9], v[8:9], v[106:107]
	v_pk_mul_f32 v[4:5], v[4:5], v[110:111]
	v_pk_mul_f32 v[0:1], v[0:1], v[114:115]
	v_pk_mul_f32 v[62:63], v[62:63], v[104:105]
	v_pk_mul_f32 v[58:59], v[58:59], v[108:109]
	v_pk_mul_f32 v[54:55], v[54:55], v[112:113]
	v_pk_mul_f32 v[50:51], v[50:51], v[116:117]
	v_pk_mul_f32 v[60:61], v[60:61], v[102:103]
	v_pk_mul_f32 v[56:57], v[56:57], v[106:107]
	v_pk_mul_f32 v[52:53], v[52:53], v[110:111]
	v_pk_mul_f32 v[48:49], v[48:49], v[114:115]
	v_pk_mul_f32 v[46:47], v[46:47], v[104:105]
	v_pk_mul_f32 v[42:43], v[42:43], v[108:109]
	v_pk_mul_f32 v[38:39], v[38:39], v[112:113]
	v_pk_mul_f32 v[34:35], v[34:35], v[116:117]
	v_pk_mul_f32 v[44:45], v[44:45], v[102:103]
	v_pk_mul_f32 v[40:41], v[40:41], v[106:107]
	v_pk_mul_f32 v[36:37], v[36:37], v[110:111]
	v_pk_mul_f32 v[32:33], v[32:33], v[114:115]
	v_pk_mul_f32 v[30:31], v[30:31], v[104:105]
	v_pk_mul_f32 v[26:27], v[26:27], v[108:109]
	v_pk_mul_f32 v[22:23], v[22:23], v[112:113]
	v_pk_mul_f32 v[18:19], v[18:19], v[116:117]
	v_pk_mul_f32 v[28:29], v[28:29], v[102:103]
	v_pk_mul_f32 v[24:25], v[24:25], v[106:107]
	v_pk_mul_f32 v[20:21], v[20:21], v[110:111]
	v_pk_mul_f32 v[16:17], v[16:17], v[114:115]
